# multi-pass RNE-to-cvt_pk rewrite (820 sites) plus mov fold, and the two hazard pads at the band softmax head removed (the hoisted V reads now supply the MFMA-to-VALU wait states)
# baseline (speedup 1.0000x reference)
.LBB0_459:
	ds_read_b64_tr_b16 v[188:189], v153 offset:9216
	ds_read_b64_tr_b16 v[190:191], v153 offset:9984
	ds_read_b64_tr_b16 v[192:193], v153 offset:9280
	ds_read_b64_tr_b16 v[194:195], v153 offset:10048
	ds_read_b64_tr_b16 v[196:197], v153 offset:12288
	ds_read_b64_tr_b16 v[198:199], v153 offset:13056
	ds_read_b64_tr_b16 v[200:201], v153 offset:12352
	ds_read_b64_tr_b16 v[202:203], v153 offset:13120
	ds_read_b64_tr_b16 v[204:205], v153 offset:15360
	ds_read_b64_tr_b16 v[206:207], v153 offset:16128
	ds_read_b64_tr_b16 v[208:209], v153 offset:15424
	ds_read_b64_tr_b16 v[210:211], v153 offset:16192
	ds_read_b64_tr_b16 v[212:213], v153 offset:18432
	ds_read_b64_tr_b16 v[214:215], v153 offset:19200
	ds_read_b64_tr_b16 v[216:217], v153 offset:18496
	ds_read_b64_tr_b16 v[218:219], v153 offset:19264
	v_max_f32_e32 v2, v51, v51
	v_max_f32_e32 v225, v50, v50
	v_max_f32_e32 v2, v225, v2
	v_max3_f32 v2, v2, v52, v53
	v_max3_f32 v2, v2, v54, v55
	v_max3_f32 v2, v2, v56, v57
	v_max3_f32 v2, v2, v58, v59
	v_max3_f32 v2, v2, v60, v61
	v_max3_f32 v2, v2, v62, v63
	v_max3_f32 v2, v2, v64, v65
	v_max3_f32 v2, v2, v66, v67
	v_max3_f32 v2, v2, v68, v69
	v_max3_f32 v2, v2, v70, v71
	v_max3_f32 v2, v2, v72, v73
	v_max3_f32 v2, v2, v74, v75
	v_max3_f32 v2, v2, v76, v77
	v_max3_f32 v2, v2, v78, v79
	v_max3_f32 v2, v2, v80, v81
	v_add_f32_e32 v2, v2, v223
	v_mov_b32_e32 v225, v2
	s_nop 1
	v_permlane32_swap_b32_e32 v225, v2
	v_max3_f32 v224, v173, v2, v225
	v_add_f32_e32 v2, 0x41000000, v173
	v_cmp_gt_f32_e32 vcc, v224, v2
	s_nop 1
	v_cndmask_b32_e32 v224, v173, v224, vcc
	v_sub_f32_e32 v2, v173, v224
	v_exp_f32_e32 v2, v2
	s_nop 0
	v_cmp_neq_f32_e32 vcc, 1.0, v2
	s_cbranch_vccz .LBB0_461
	v_mul_f32_e32 v48, v2, v48
	v_mul_f32_e32 v49, v2, v49
	v_mul_f32_e32 v46, v2, v46
	v_mul_f32_e32 v47, v2, v47
	v_mul_f32_e32 v44, v2, v44
	v_mul_f32_e32 v45, v2, v45
	v_mul_f32_e32 v42, v2, v42
	v_mul_f32_e32 v43, v2, v43
	v_mul_f32_e32 v40, v2, v40
	v_mul_f32_e32 v41, v2, v41
	v_mul_f32_e32 v38, v2, v38
	v_mul_f32_e32 v39, v2, v39
	v_mul_f32_e32 v36, v2, v36
	v_mul_f32_e32 v37, v2, v37
	v_mul_f32_e32 v34, v2, v34
	v_mul_f32_e32 v35, v2, v35
	v_mul_f32_e32 v32, v2, v32
	v_mul_f32_e32 v33, v2, v33
	v_mul_f32_e32 v30, v2, v30
	v_mul_f32_e32 v31, v2, v31
	v_mul_f32_e32 v28, v2, v28
	v_mul_f32_e32 v29, v2, v29
	v_mul_f32_e32 v26, v2, v26
	v_mul_f32_e32 v27, v2, v27
	v_mul_f32_e32 v24, v2, v24
	v_mul_f32_e32 v25, v2, v25
	v_mul_f32_e32 v22, v2, v22
	v_mul_f32_e32 v23, v2, v23
	v_mul_f32_e32 v20, v2, v20
	v_mul_f32_e32 v21, v2, v21
	v_mul_f32_e32 v18, v2, v18
	v_mul_f32_e32 v19, v2, v19

.LBB0_487:
	s_and_b64 vcc, exec, s[16:17]
	s_cbranch_vccz .LBB0_489
	s_mov_b64 s[16:17], s[0:1]
	s_load_dwordx2 s[26:27], s[16:17], 0x78
	s_mov_b64 s[16:17], s[0:1]
	s_load_dwordx2 s[60:61], s[16:17], 0xa8
	s_mov_b64 s[16:17], s[0:1]
	s_load_dwordx2 s[16:17], s[16:17], 0x20
	s_waitcnt lgkmcnt(0)
	s_add_u32 s16, s16, 0x1000
	s_addc_u32 s17, s17, 0
	s_add_i32 s24, s23, 32
	s_and_b32 s62, s24, 0xff
	s_mulk_i32 s62, 0xab
	s_lshr_b32 s62, s62, 10
	s_mul_i32 s63, s62, 6
	s_sub_i32 s24, s24, s63
	s_and_b32 s24, s24, 0xff
	v_lshl_or_b32 v6, s24, 7, v155
	v_lshlrev_b32_e32 v2, 11, v6
	v_lshl_add_u64 v[4:5], s[60:61], 0, v[2:3]
	s_lshl_b32 s24, s62, 7
	v_lshl_add_u64 v[4:5], v[4:5], 0, s[24:25]
	v_lshlrev_b32_e32 v2, 1, v116
	s_waitcnt vmcnt(4)
	v_lshl_add_u64 v[96:97], v[4:5], 0, v[2:3]
	v_lshl_or_b32 v78, s62, 6, v116
	v_lshlrev_b32_e32 v2, 2, v6
	v_lshl_add_u64 v[76:77], s[26:27], 0, v[2:3]
	v_mul_u32_u24_e32 v2, 0x300, v78
	v_lshlrev_b32_e32 v2, 2, v2
	v_mad_u64_u32 v[4:5], s[26:27], v78, s68, v[76:77]
	v_lshl_add_u64 v[74:75], v[76:77], 0, v[2:3]
	global_load_dwordx4 v[48:51], v[4:5], off nt
	global_load_dwordx4 v[44:47], v[74:75], off offset:3072 nt
	v_add_co_u32_e32 v4, vcc, s69, v74
	s_movk_i32 s24, 0x3000
	s_nop 0
	v_addc_co_u32_e32 v5, vcc, 0, v75, vcc
	v_add_co_u32_e32 v6, vcc, s81, v74
	v_lshlrev_b32_e32 v2, 2, v78
	s_nop 0
	v_addc_co_u32_e32 v7, vcc, 0, v75, vcc
	global_load_dwordx4 v[56:59], v[4:5], off offset:2048 nt
	global_load_dwordx4 v[52:55], v[6:7], off offset:1024 nt
	v_add_co_u32_e32 v4, vcc, s24, v74
	global_load_dwordx4 v[60:63], v2, s[16:17] offset:16
	global_load_dwordx4 v[68:71], v2, s[16:17]
	v_addc_co_u32_e32 v5, vcc, 0, v75, vcc
	global_load_dwordx4 v[80:83], v[4:5], off nt
	global_load_dwordx4 v[64:67], v[4:5], off offset:3072 nt
	v_add_co_u32_e32 v4, vcc, s70, v74
	s_mov_b32 s24, 0xc000
	s_nop 0
	v_addc_co_u32_e32 v5, vcc, 0, v75, vcc
	global_load_dwordx4 v[84:87], v[4:5], off offset:2048 nt
	v_add_co_u32_e32 v4, vcc, s82, v74
	v_or_b32_e32 v2, 16, v78
	s_nop 0
	v_addc_co_u32_e32 v5, vcc, 0, v75, vcc
	global_load_dwordx4 v[88:91], v[4:5], off offset:1024 nt
	v_add_co_u32_e32 v14, vcc, s24, v74
	s_mov_b32 s24, 0xd000
	s_nop 0
	v_addc_co_u32_e32 v15, vcc, 0, v75, vcc
	v_add_co_u32_e32 v16, vcc, s24, v74
	s_mov_b32 s24, 0xe000
	s_nop 0
	v_addc_co_u32_e32 v17, vcc, 0, v75, vcc
	v_add_co_u32_e32 v18, vcc, s24, v74
	s_mov_b32 s24, 0xf000
	s_nop 0
	v_addc_co_u32_e32 v19, vcc, 0, v75, vcc
	v_add_co_u32_e32 v28, vcc, s24, v74
	s_mov_b32 s24, 0x10000
	s_nop 0
	v_addc_co_u32_e32 v29, vcc, 0, v75, vcc
	v_add_co_u32_e32 v30, vcc, s24, v74
	v_lshlrev_b32_e32 v8, 2, v2
	s_mov_b64 s[26:27], 0x5000000
	v_addc_co_u32_e32 v31, vcc, 0, v75, vcc
	global_load_dwordx4 v[4:7], v8, s[16:17] offset:16
	s_nop 0
	global_load_dwordx4 v[8:11], v8, s[16:17]
	v_lshl_add_u64 v[72:73], v[96:97], 0, s[26:27]
	v_mad_u64_u32 v[12:13], s[26:27], v2, s68, v[76:77]
	v_add_co_u32_e32 v92, vcc, s83, v74
	s_mov_b32 s24, 0x5001000
	s_nop 0
	v_addc_co_u32_e32 v93, vcc, 0, v75, vcc
	global_load_dwordx4 v[20:23], v[12:13], off nt
	global_load_dwordx4 v[32:35], v[14:15], off offset:3072 nt
	global_load_dwordx4 v[40:43], v[16:17], off offset:2048 nt
	global_load_dwordx4 v[36:39], v[18:19], off offset:1024 nt
	global_load_dwordx4 v[24:27], v[28:29], off nt
	s_nop 0
	global_load_dwordx4 v[12:15], v[28:29], off offset:3072 nt
	s_nop 0
	global_load_dwordx4 v[28:31], v[30:31], off offset:2048 nt
	s_nop 0
	global_load_dwordx4 v[16:19], v[92:93], off offset:1024 nt
	s_waitcnt vmcnt(19)
	s_waitcnt vmcnt(18)
	v_mov_b32_e32 v94, v44
	s_waitcnt vmcnt(17)
	s_waitcnt vmcnt(16)
	v_mov_b32_e32 v95, v52
	s_waitcnt vmcnt(15)
	v_mov_b32_e32 v101, v62
	v_mov_b32_e32 v62, v61
	s_waitcnt vmcnt(14)
	v_mov_b32_e32 v98, v68
	v_mov_b32_e32 v99, v70
	s_waitcnt vmcnt(12)
	v_mov_b32_e32 v102, v64
	v_mov_b32_e32 v70, v69
	v_mov_b32_e32 v100, v60
	v_mul_f32_e32 v92, v98, v48
	v_mul_f32_e32 v93, v99, v56
	v_pk_mul_f32 v[68:69], v[94:95], v[70:71]
	s_waitcnt vmcnt(11)
	v_mul_f32_e32 v94, v100, v80
	v_mul_f32_e32 v95, v101, v84
	s_waitcnt vmcnt(10)
	v_mov_b32_e32 v103, v88
	v_pk_mul_f32 v[60:61], v[102:103], v[62:63]
	v_cvt_pk_bf16_f32 v92, v92, v68
	v_mov_b32_e32 v52, v45
	v_cvt_pk_bf16_f32 v94, v94, v60
	v_mov_b32_e32 v56, v49
	v_pk_mul_f32 v[44:45], v[52:53], v[70:71]
	v_mov_b32_e32 v88, v65
	v_cvt_pk_bf16_f32 v93, v93, v69
	v_pk_mul_f32 v[48:49], v[56:57], v[98:99]
	v_mov_b32_e32 v84, v81
	v_pk_mul_f32 v[56:57], v[88:89], v[62:63]
	v_cvt_pk_bf16_f32 v95, v95, v61
	v_pk_mul_f32 v[52:53], v[84:85], v[100:101]
	v_add_co_u32_e32 v60, vcc, s24, v96
	v_addc_co_u32_e32 v61, vcc, 0, v97, vcc
	global_store_dwordx4 v[60:61], v[92:95], off offset:-4096
	s_nop 1
	v_cvt_pk_bf16_f32 v93, v49, v45
	s_nop 1
	v_cvt_pk_bf16_f32 v92, v48, v44
	v_cvt_pk_bf16_f32 v95, v53, v57
	v_cvt_pk_bf16_f32 v94, v52, v56
	v_mul_f32_e32 v48, v70, v46
	v_mul_f32_e32 v49, v71, v54
	v_mov_b32_e32 v44, v50
	v_mul_f32_e32 v52, v100, v82
	v_mul_f32_e32 v53, v101, v86
	v_mul_f32_e32 v56, v62, v66
	v_mul_f32_e32 v57, v63, v90
	v_bfe_u32 v50, v49, 16, 1
	v_mul_f32_e32 v44, v98, v44
	v_mul_f32_e32 v45, v99, v58
	v_bfe_u32 v2, v57, 16, 1
	v_bfe_u32 v46, v56, 16, 1
	v_add3_u32 v49, v49, v50, s76
	v_bfe_u32 v50, v52, 16, 1
	v_add3_u32 v46, v56, v46, s76
	v_add3_u32 v2, v57, v2, s76
	v_bfe_u32 v54, v53, 16, 1
	v_bfe_u32 v57, v45, 16, 1
	v_add3_u32 v50, v52, v50, s76
	v_add3_u32 v53, v53, v54, s76
	v_add3_u32 v45, v45, v57, s76
	v_lshrrev_b32_e32 v50, 16, v50
	v_mov_b32_e32 v54, v47
	v_mov_b32_e32 v90, v67
	global_store_dwordx4 v[72:73], v[92:95], off offset:2048
	v_lshrrev_b32_e32 v52, 16, v53
	v_lshrrev_b32_e32 v45, 16, v45
	v_and_or_b32 v94, v46, s77, v50
	v_mov_b32_e32 v58, v51
	v_pk_mul_f32 v[46:47], v[54:55], v[70:71]
	v_mov_b32_e32 v86, v83
	v_pk_mul_f32 v[50:51], v[90:91], v[62:63]
	v_and_or_b32 v95, v2, s77, v52
	v_and_or_b32 v93, v49, s77, v45
	v_cvt_pk_bf16_f32 v92, v44, v48
	v_pk_mul_f32 v[44:45], v[58:59], v[98:99]
	v_pk_mul_f32 v[48:49], v[86:87], v[100:101]
	v_bfe_u32 v2, v51, 16, 1
	v_bfe_u32 v52, v50, 16, 1
	v_bfe_u32 v53, v47, 16, 1
	v_bfe_u32 v54, v46, 16, 1
	v_add3_u32 v50, v50, v52, s76
	v_add3_u32 v2, v51, v2, s76
	v_add3_u32 v51, v46, v54, s76
	v_add3_u32 v52, v47, v53, s76
	v_bfe_u32 v46, v48, 16, 1
	v_bfe_u32 v47, v49, 16, 1
	v_bfe_u32 v53, v44, 16, 1
	v_bfe_u32 v54, v45, 16, 1
	v_add3_u32 v47, v49, v47, s76
	v_add3_u32 v46, v48, v46, s76
	v_add3_u32 v45, v45, v54, s76
	v_add3_u32 v44, v44, v53, s76
	v_lshrrev_b32_e32 v46, 16, v46
	v_lshrrev_b32_e32 v47, 16, v47
	v_lshrrev_b32_e32 v44, 16, v44
	v_lshrrev_b32_e32 v45, 16, v45
	v_and_or_b32 v47, v2, s77, v47
	v_and_or_b32 v46, v50, s77, v46
	v_and_or_b32 v45, v52, s77, v45
	v_and_or_b32 v44, v51, s77, v44
	global_store_dwordx4 v[60:61], v[44:47], off offset:2048
	s_waitcnt vmcnt(11)
	v_mov_b32_e32 v49, v10
	v_mov_b32_e32 v10, v9
	s_waitcnt vmcnt(9)
	v_mov_b32_e32 v46, v32
	s_waitcnt vmcnt(7)
	v_mov_b32_e32 v47, v36
	v_mov_b32_e32 v48, v8
	v_pk_mul_f32 v[8:9], v[46:47], v[10:11]
	v_mov_b32_e32 v51, v6
	s_waitcnt vmcnt(5)
	v_mov_b32_e32 v52, v12
	s_waitcnt vmcnt(3)
	v_mov_b32_e32 v53, v16
	v_mov_b32_e32 v6, v5
	v_mul_f32_e32 v44, v48, v20
	v_mul_f32_e32 v45, v49, v40
	v_mov_b32_e32 v50, v4
	v_pk_mul_f32 v[4:5], v[52:53], v[6:7]
	v_bfe_u32 v16, v9, 16, 1
	v_mul_f32_e32 v46, v50, v24
	v_mul_f32_e32 v47, v51, v28
	v_add3_u32 v9, v9, v16, s76
	v_bfe_u32 v20, v45, 16, 1
	v_add3_u32 v20, v45, v20, s76
	v_lshrrev_b32_e32 v20, 16, v20
	v_mov_b32_e32 v36, v33
	v_and_or_b32 v45, v9, s77, v20
	v_cvt_pk_bf16_f32 v44, v44, v8
	v_mov_b32_e32 v40, v21
	v_pk_mul_f32 v[8:9], v[36:37], v[10:11]
	v_mov_b32_e32 v16, v13
	v_cvt_pk_bf16_f32 v47, v47, v5
	v_cvt_pk_bf16_f32 v46, v46, v4
	v_pk_mul_f32 v[4:5], v[40:41], v[48:49]
	v_mov_b32_e32 v28, v25
	v_pk_mul_f32 v[12:13], v[16:17], v[6:7]
	v_pk_mul_f32 v[20:21], v[28:29], v[50:51]
	v_bfe_u32 v16, v12, 16, 1
	v_bfe_u32 v2, v13, 16, 1
	v_add3_u32 v12, v12, v16, s76
	v_bfe_u32 v16, v21, 16, 1
	v_add3_u32 v2, v13, v2, s76
	v_bfe_u32 v13, v20, 16, 1
	v_add3_u32 v16, v21, v16, s76
	global_store_dwordx4 v[72:73], v[44:47], off offset:32
	v_add3_u32 v13, v20, v13, s76
	v_lshrrev_b32_e32 v16, 16, v16
	v_cvt_pk_bf16_f32 v45, v5, v9
	v_cvt_pk_bf16_f32 v44, v4, v8
	v_lshrrev_b32_e32 v13, 16, v13
	v_and_or_b32 v47, v2, s77, v16
	v_mul_f32_e32 v8, v10, v34
	v_mul_f32_e32 v9, v11, v38
	v_and_or_b32 v46, v12, s77, v13
	v_mul_f32_e32 v4, v48, v22
	v_mul_f32_e32 v5, v49, v42
	v_mul_f32_e32 v16, v6, v14
	v_mul_f32_e32 v17, v7, v18
	v_bfe_u32 v18, v9, 16, 1
	v_bfe_u32 v20, v8, 16, 1
	v_mul_f32_e32 v12, v50, v26
	v_mul_f32_e32 v13, v51, v30
	v_add3_u32 v8, v8, v20, s76
	v_add3_u32 v9, v9, v18, s76
	v_bfe_u32 v18, v4, 16, 1
	v_bfe_u32 v20, v5, 16, 1
	v_add3_u32 v5, v5, v20, s76
	v_add3_u32 v4, v4, v18, s76
	v_lshrrev_b32_e32 v4, 16, v4
	v_lshrrev_b32_e32 v5, 16, v5
	v_mov_b32_e32 v38, v35
	v_mov_b32_e32 v18, v15
	global_store_dwordx4 v[72:73], v[44:47], off offset:2080
	s_nop 1
	v_and_or_b32 v45, v9, s77, v5
	s_nop 1
	v_and_or_b32 v44, v8, s77, v4
	v_mov_b32_e32 v42, v23
	v_pk_mul_f32 v[8:9], v[38:39], v[10:11]
	v_mov_b32_e32 v30, v27
	v_pk_mul_f32 v[6:7], v[18:19], v[6:7]
	v_cvt_pk_bf16_f32 v47, v13, v17
	v_cvt_pk_bf16_f32 v46, v12, v16
	v_pk_mul_f32 v[4:5], v[42:43], v[48:49]
	v_pk_mul_f32 v[10:11], v[30:31], v[50:51]
	v_bfe_u32 v2, v7, 16, 1
	v_bfe_u32 v12, v6, 16, 1
	v_add3_u32 v6, v6, v12, s76
	v_add3_u32 v2, v7, v2, s76
	v_bfe_u32 v7, v10, 16, 1
	v_bfe_u32 v12, v11, 16, 1
	v_add3_u32 v11, v11, v12, s76
	v_add3_u32 v7, v10, v7, s76
	v_lshrrev_b32_e32 v10, 16, v7
	v_lshrrev_b32_e32 v7, 16, v11
	v_and_or_b32 v7, v2, s77, v7
	v_and_or_b32 v6, v6, s77, v10
	v_cvt_pk_bf16_f32 v5, v5, v9
	v_cvt_pk_bf16_f32 v4, v4, v8
	s_mov_b32 s24, 0x18000
	global_store_dwordx4 v[60:61], v[4:7], off offset:2080
	v_or_b32_e32 v2, 32, v78
	global_store_dwordx4 v[60:61], v[92:95], off
	v_add_co_u32_e32 v6, vcc, s24, v74
	global_store_dwordx4 v[60:61], v[44:47], off offset:32
	v_mad_u64_u32 v[4:5], s[26:27], v2, s68, v[76:77]
	v_addc_co_u32_e32 v7, vcc, 0, v75, vcc
	s_mov_b32 s24, 0x19000
	global_load_dwordx4 v[44:47], v[4:5], off nt
	global_load_dwordx4 v[48:51], v[6:7], off offset:3072 nt
	v_add_co_u32_e32 v4, vcc, s24, v74
	s_mov_b32 s24, 0x1a000
	s_nop 0
	v_addc_co_u32_e32 v5, vcc, 0, v75, vcc
	v_add_co_u32_e32 v6, vcc, s24, v74
	s_mov_b32 s24, 0x1b000
	s_nop 0
	v_addc_co_u32_e32 v7, vcc, 0, v75, vcc
	global_load_dwordx4 v[52:55], v[4:5], off offset:2048 nt
	global_load_dwordx4 v[56:59], v[6:7], off offset:1024 nt
	v_add_co_u32_e32 v4, vcc, s24, v74
	v_lshlrev_b32_e32 v2, 2, v2
	s_nop 0
	v_addc_co_u32_e32 v5, vcc, 0, v75, vcc
	s_mov_b32 s24, 0x1c000
	global_load_dwordx4 v[62:65], v2, s[16:17] offset:16
	global_load_dwordx4 v[66:69], v2, s[16:17]
	global_load_dwordx4 v[80:83], v[4:5], off nt
	global_load_dwordx4 v[84:87], v[4:5], off offset:3072 nt
	v_add_co_u32_e32 v4, vcc, s24, v74
	s_mov_b32 s24, 0x1d000
	s_nop 0
	v_addc_co_u32_e32 v5, vcc, 0, v75, vcc
	global_load_dwordx4 v[88:91], v[4:5], off offset:2048 nt
	v_add_co_u32_e32 v4, vcc, s24, v74
	s_mov_b32 s24, 0x24000
	s_nop 0
	v_addc_co_u32_e32 v5, vcc, 0, v75, vcc
	global_load_dwordx4 v[92:95], v[4:5], off offset:1024 nt
	v_add_co_u32_e32 v6, vcc, s24, v74
	s_mov_b32 s24, 0x26000
	s_nop 0
	v_addc_co_u32_e32 v7, vcc, 0, v75, vcc
	v_add_co_u32_e32 v12, vcc, s84, v74
	v_or_b32_e32 v2, 48, v78
	s_nop 0
	v_addc_co_u32_e32 v13, vcc, 0, v75, vcc
	v_add_co_u32_e32 v14, vcc, s24, v74
	s_mov_b32 s24, 0x28000
	s_nop 0
	v_addc_co_u32_e32 v15, vcc, 0, v75, vcc
	v_add_co_u32_e32 v16, vcc, s85, v74
	v_mad_u64_u32 v[4:5], s[26:27], v2, s68, v[76:77]
	s_nop 0
	v_addc_co_u32_e32 v17, vcc, 0, v75, vcc
	v_add_co_u32_e32 v28, vcc, s24, v74
	s_mov_b32 s24, 0x29000
	s_nop 0
	v_addc_co_u32_e32 v29, vcc, 0, v75, vcc
	v_add_co_u32_e32 v30, vcc, s24, v74
	v_lshlrev_b32_e32 v2, 2, v2
	s_nop 0
	v_addc_co_u32_e32 v31, vcc, 0, v75, vcc
	global_load_dwordx4 v[8:11], v[4:5], off nt
	s_nop 0
	global_load_dwordx4 v[4:7], v[6:7], off offset:3072 nt
	s_nop 0
	global_load_dwordx4 v[20:23], v[12:13], off offset:2048 nt
	s_nop 0
	global_load_dwordx4 v[12:15], v[14:15], off offset:1024 nt
	s_nop 0
	global_load_dwordx4 v[24:27], v[16:17], off nt
	s_nop 0
	global_load_dwordx4 v[16:19], v[16:17], off offset:3072 nt
	s_nop 0
	global_load_dwordx4 v[32:35], v[28:29], off offset:2048 nt
	s_nop 0
	global_load_dwordx4 v[28:31], v[30:31], off offset:1024 nt
	s_nop 0
	global_load_dwordx4 v[36:39], v2, s[16:17] offset:16
	global_load_dwordx4 v[40:43], v2, s[16:17]
	s_waitcnt vmcnt(19)
	s_waitcnt vmcnt(18)
	v_mov_b32_e32 v74, v48
	s_waitcnt vmcnt(17)
	s_waitcnt vmcnt(16)
	v_mov_b32_e32 v75, v56
	s_waitcnt vmcnt(15)
	v_mov_b32_e32 v96, v62
	s_waitcnt vmcnt(14)
	v_mov_b32_e32 v79, v68
	v_mov_b32_e32 v68, v67
	v_mov_b32_e32 v78, v66
	v_pk_mul_f32 v[66:67], v[74:75], v[68:69]
	s_waitcnt vmcnt(13)
	v_mov_b32_e32 v97, v64
	s_waitcnt vmcnt(12)
	v_mov_b32_e32 v76, v84
	s_waitcnt vmcnt(11)
	v_mov_b32_e32 v64, v63
	v_mul_f32_e32 v74, v96, v80
	v_mul_f32_e32 v75, v97, v88
	v_mul_f32_e32 v70, v78, v44
	v_mul_f32_e32 v71, v79, v52
	v_bfe_u32 v56, v74, 16, 1
	s_waitcnt vmcnt(10)
	v_mov_b32_e32 v77, v92
	v_pk_mul_f32 v[62:63], v[76:77], v[64:65]
	v_bfe_u32 v2, v63, 16, 1
	v_bfe_u32 v44, v62, 16, 1
	v_add3_u32 v2, v63, v2, s76
	v_add3_u32 v56, v74, v56, s76
	v_add3_u32 v44, v62, v44, s76
	v_lshrrev_b32_e32 v56, 16, v56
	v_bfe_u32 v62, v75, 16, 1
	v_and_or_b32 v76, v44, s77, v56
	v_mov_b32_e32 v56, v49
	v_add3_u32 v62, v75, v62, s76
	v_cvt_pk_bf16_f32 v75, v71, v67
	v_cvt_pk_bf16_f32 v74, v70, v66
	v_mov_b32_e32 v52, v45
	v_pk_mul_f32 v[48:49], v[56:57], v[68:69]
	v_mov_b32_e32 v92, v85
	v_lshrrev_b32_e32 v62, 16, v62
	v_pk_mul_f32 v[44:45], v[52:53], v[78:79]
	v_mov_b32_e32 v88, v81
	v_pk_mul_f32 v[56:57], v[92:93], v[64:65]
	v_and_or_b32 v77, v2, s77, v62
	v_pk_mul_f32 v[52:53], v[88:89], v[96:97]
	global_store_dwordx4 v[72:73], v[74:77], off offset:64
	s_nop 1
	v_cvt_pk_bf16_f32 v75, v45, v49
	s_nop 1
	v_cvt_pk_bf16_f32 v74, v44, v48
	v_cvt_pk_bf16_f32 v77, v53, v57
	v_cvt_pk_bf16_f32 v76, v52, v56
	v_mul_f32_e32 v48, v68, v50
	v_mul_f32_e32 v49, v69, v58
	v_mul_f32_e32 v52, v96, v82
	v_mul_f32_e32 v53, v97, v90
	v_mul_f32_e32 v56, v64, v86
	v_mul_f32_e32 v57, v65, v94
	v_bfe_u32 v50, v49, 16, 1
	v_mul_f32_e32 v44, v78, v46
	v_mul_f32_e32 v45, v79, v54
	v_bfe_u32 v2, v57, 16, 1
	v_bfe_u32 v46, v56, 16, 1
	v_bfe_u32 v54, v48, 16, 1
	v_add3_u32 v49, v49, v50, s76
	v_bfe_u32 v50, v52, 16, 1
	v_add3_u32 v48, v48, v54, s76
	v_add3_u32 v46, v56, v46, s76
	v_add3_u32 v2, v57, v2, s76
	v_bfe_u32 v54, v53, 16, 1
	v_bfe_u32 v56, v44, 16, 1
	v_bfe_u32 v57, v45, 16, 1
	v_add3_u32 v50, v52, v50, s76
	v_add3_u32 v53, v53, v54, s76
	v_add3_u32 v45, v45, v57, s76
	v_add3_u32 v44, v44, v56, s76
	v_lshrrev_b32_e32 v50, 16, v50
	v_mov_b32_e32 v58, v51
	v_mov_b32_e32 v94, v87
	global_store_dwordx4 v[72:73], v[74:77], off offset:2112
	v_lshrrev_b32_e32 v52, 16, v53
	v_lshrrev_b32_e32 v44, 16, v44
	v_lshrrev_b32_e32 v45, 16, v45
	v_and_or_b32 v76, v46, s77, v50
	v_mov_b32_e32 v54, v47
	v_pk_mul_f32 v[46:47], v[58:59], v[68:69]
	v_mov_b32_e32 v90, v83
	v_pk_mul_f32 v[50:51], v[94:95], v[64:65]
	v_and_or_b32 v77, v2, s77, v52
	v_and_or_b32 v75, v49, s77, v45
	v_and_or_b32 v74, v48, s77, v44
	v_pk_mul_f32 v[44:45], v[54:55], v[78:79]
	v_pk_mul_f32 v[48:49], v[90:91], v[96:97]
	v_bfe_u32 v2, v51, 16, 1
	v_bfe_u32 v52, v50, 16, 1
	v_bfe_u32 v53, v47, 16, 1
	v_bfe_u32 v54, v46, 16, 1
	v_add3_u32 v54, v46, v54, s76
	v_add3_u32 v53, v47, v53, s76
	v_add3_u32 v46, v50, v52, s76
	v_add3_u32 v2, v51, v2, s76
	v_bfe_u32 v47, v48, 16, 1
	v_bfe_u32 v50, v49, 16, 1
	v_bfe_u32 v51, v44, 16, 1
	v_bfe_u32 v52, v45, 16, 1
	v_add3_u32 v49, v49, v50, s76
	v_add3_u32 v47, v48, v47, s76
	v_add3_u32 v45, v45, v52, s76
	v_add3_u32 v44, v44, v51, s76
	v_lshrrev_b32_e32 v48, 16, v47
	v_lshrrev_b32_e32 v47, 16, v49
	v_lshrrev_b32_e32 v44, 16, v44
	v_lshrrev_b32_e32 v45, 16, v45
	v_and_or_b32 v47, v2, s77, v47
	v_and_or_b32 v46, v46, s77, v48
	v_and_or_b32 v45, v53, s77, v45
	v_and_or_b32 v44, v54, s77, v44
	global_store_dwordx4 v[60:61], v[44:47], off offset:2112
	s_waitcnt vmcnt(3)
	v_mov_b32_e32 v48, v40
	v_mov_b32_e32 v49, v42
	v_mov_b32_e32 v46, v4
	v_mov_b32_e32 v47, v12
	v_mov_b32_e32 v42, v41
	v_mul_f32_e32 v44, v48, v8
	v_mul_f32_e32 v45, v49, v20
	v_pk_mul_f32 v[40:41], v[46:47], v[42:43]
	v_mov_b32_e32 v50, v36
	v_mov_b32_e32 v51, v38
	v_mul_f32_e32 v46, v50, v24
	v_mul_f32_e32 v47, v51, v32
	v_mov_b32_e32 v52, v16
	v_mov_b32_e32 v53, v28
	v_mov_b32_e32 v38, v37
	v_pk_mul_f32 v[36:37], v[52:53], v[38:39]
	v_cvt_pk_bf16_f32 v44, v44, v40
	v_mov_b32_e32 v12, v5
	v_cvt_pk_bf16_f32 v47, v47, v37
	v_cvt_pk_bf16_f32 v46, v46, v36
	v_cvt_pk_bf16_f32 v45, v45, v41
	v_mov_b32_e32 v20, v9
	v_pk_mul_f32 v[4:5], v[12:13], v[42:43]
	v_mov_b32_e32 v28, v17
	v_pk_mul_f32 v[8:9], v[20:21], v[48:49]
	v_mov_b32_e32 v32, v25
	v_pk_mul_f32 v[16:17], v[28:29], v[38:39]
	v_pk_mul_f32 v[12:13], v[32:33], v[50:51]
	global_store_dwordx4 v[72:73], v[44:47], off offset:96
	s_nop 1
	v_cvt_pk_bf16_f32 v45, v9, v5
	s_nop 1
	v_cvt_pk_bf16_f32 v44, v8, v4
	v_cvt_pk_bf16_f32 v47, v13, v17
	v_cvt_pk_bf16_f32 v46, v12, v16
	v_mul_f32_e32 v8, v42, v6
	v_mul_f32_e32 v9, v43, v14
	v_mov_b32_e32 v4, v10
	v_mul_f32_e32 v12, v50, v26
	v_mul_f32_e32 v13, v51, v34
	v_mul_f32_e32 v16, v38, v18
	v_mul_f32_e32 v17, v39, v30
	v_bfe_u32 v10, v9, 16, 1
	v_mul_f32_e32 v4, v48, v4
	v_mul_f32_e32 v5, v49, v22
	v_bfe_u32 v2, v17, 16, 1
	v_bfe_u32 v6, v16, 16, 1
	v_add3_u32 v9, v9, v10, s76
	v_bfe_u32 v10, v12, 16, 1
	v_add3_u32 v6, v16, v6, s76
	v_add3_u32 v2, v17, v2, s76
	v_bfe_u32 v14, v13, 16, 1
	v_bfe_u32 v17, v5, 16, 1
	v_add3_u32 v10, v12, v10, s76
	v_add3_u32 v13, v13, v14, s76
	v_add3_u32 v5, v5, v17, s76
	v_lshrrev_b32_e32 v10, 16, v10
	v_mov_b32_e32 v14, v7
	v_mov_b32_e32 v30, v19
	global_store_dwordx4 v[72:73], v[44:47], off offset:2144
	v_lshrrev_b32_e32 v12, 16, v13
	v_lshrrev_b32_e32 v5, 16, v5
	v_and_or_b32 v46, v6, s77, v10
	v_mov_b32_e32 v22, v11
	v_pk_mul_f32 v[6:7], v[14:15], v[42:43]
	v_mov_b32_e32 v34, v27
	v_pk_mul_f32 v[10:11], v[30:31], v[38:39]
	v_and_or_b32 v47, v2, s77, v12
	v_and_or_b32 v45, v9, s77, v5
	v_cvt_pk_bf16_f32 v44, v4, v8
	v_pk_mul_f32 v[4:5], v[22:23], v[48:49]
	v_pk_mul_f32 v[8:9], v[34:35], v[50:51]
	v_bfe_u32 v2, v11, 16, 1
	v_bfe_u32 v12, v10, 16, 1
	v_bfe_u32 v13, v7, 16, 1
	v_bfe_u32 v14, v6, 16, 1
	v_add3_u32 v14, v6, v14, s76
	v_add3_u32 v13, v7, v13, s76
	v_add3_u32 v6, v10, v12, s76
	v_add3_u32 v2, v11, v2, s76
	v_bfe_u32 v7, v8, 16, 1
	v_bfe_u32 v10, v9, 16, 1
	v_bfe_u32 v11, v4, 16, 1
	v_bfe_u32 v12, v5, 16, 1
	v_add3_u32 v9, v9, v10, s76
	v_add3_u32 v7, v8, v7, s76
	v_add3_u32 v5, v5, v12, s76
	v_add3_u32 v4, v4, v11, s76
	v_lshrrev_b32_e32 v8, 16, v7
	v_lshrrev_b32_e32 v7, 16, v9
	v_lshrrev_b32_e32 v4, 16, v4
	v_lshrrev_b32_e32 v5, 16, v5
	v_and_or_b32 v7, v2, s77, v7
	v_and_or_b32 v6, v6, s77, v8
	v_and_or_b32 v5, v13, s77, v5
	v_and_or_b32 v4, v14, s77, v4
	global_store_dwordx4 v[60:61], v[74:77], off offset:64
	global_store_dwordx4 v[60:61], v[44:47], off offset:96
	global_store_dwordx4 v[60:61], v[4:7], off offset:2144

.LBB0_507:
	s_waitcnt vmcnt(11)
	s_waitcnt vmcnt(9)
	v_mul_f32_e32 v94, v80, v64
	v_mul_f32_e32 v95, v81, v72
	s_waitcnt vmcnt(8)
	v_mul_f32_e32 v42, v76, v56
	v_mul_f32_e32 v43, v77, v60
	v_mul_f32_e32 v96, v90, v52
	v_mul_f32_e32 v97, v91, v68
	v_mul_f32_e32 v86, v92, v44
	v_mul_f32_e32 v87, v93, v48
	v_bfe_u32 v60, v42, 16, 1
	v_add3_u32 v42, v42, v60, s76
	v_bfe_u32 v56, v86, 16, 1
	v_cvt_pk_bf16_f32 v96, v94, v96
	v_mov_b32_e32 v48, v45
	v_mov_b32_e32 v68, v53
	v_add3_u32 v56, v86, v56, s76
	v_lshrrev_b32_e32 v42, 16, v42
	v_cvt_pk_bf16_f32 v97, v95, v97
	v_cvt_pk_bf16_f32 v95, v43, v87
	v_mov_b32_e32 v60, v57
	v_pk_mul_f32 v[44:45], v[48:49], v[92:93]
	v_mov_b32_e32 v72, v65
	v_pk_mul_f32 v[52:53], v[68:69], v[90:91]
	v_and_or_b32 v94, v56, s77, v42
	v_pk_mul_f32 v[42:43], v[60:61], v[76:77]
	v_pk_mul_f32 v[48:49], v[72:73], v[80:81]
	v_bfe_u32 v56, v53, 16, 1
	v_bfe_u32 v57, v52, 16, 1
	v_bfe_u32 v60, v45, 16, 1
	v_bfe_u32 v61, v44, 16, 1
	v_add3_u32 v61, v44, v61, s76
	v_add3_u32 v60, v45, v60, s76
	v_add3_u32 v44, v52, v57, s76
	v_add3_u32 v45, v53, v56, s76
	v_bfe_u32 v52, v42, 16, 1
	v_bfe_u32 v53, v43, 16, 1
	v_bfe_u32 v56, v48, 16, 1
	v_bfe_u32 v57, v49, 16, 1
	v_add3_u32 v49, v49, v57, s76
	v_add3_u32 v48, v48, v56, s76
	v_add3_u32 v43, v43, v53, s76
	v_add3_u32 v42, v42, v52, s76
	v_lshrrev_b32_e32 v42, 16, v42
	v_lshrrev_b32_e32 v43, 16, v43
	v_lshrrev_b32_e32 v48, 16, v48
	v_lshrrev_b32_e32 v49, 16, v49
	v_and_or_b32 v45, v45, s77, v49
	v_and_or_b32 v44, v44, s77, v48
	v_and_or_b32 v43, v60, s77, v43
	v_and_or_b32 v42, v61, s77, v42
	global_store_dwordx4 v[84:85], v[42:45], off offset:2048
	s_nop 1
	v_mul_f32_e32 v44, v92, v46
	s_nop 1
	v_mul_f32_e32 v45, v93, v50
	v_mul_f32_e32 v52, v90, v54
	v_mul_f32_e32 v53, v91, v70
	v_mul_f32_e32 v42, v76, v58
	v_mul_f32_e32 v43, v77, v62
	v_mul_f32_e32 v48, v80, v66
	v_mul_f32_e32 v49, v81, v74
	v_bfe_u32 v46, v53, 16, 1
	v_bfe_u32 v50, v52, 16, 1
	v_bfe_u32 v54, v45, 16, 1
	v_bfe_u32 v56, v44, 16, 1
	v_add3_u32 v56, v44, v56, s76
	v_add3_u32 v54, v45, v54, s76
	v_add3_u32 v44, v52, v50, s76
	v_add3_u32 v45, v53, v46, s76
	v_bfe_u32 v46, v42, 16, 1
	v_bfe_u32 v50, v43, 16, 1
	v_bfe_u32 v52, v48, 16, 1
	v_bfe_u32 v53, v49, 16, 1
	v_add3_u32 v49, v49, v53, s76
	v_add3_u32 v48, v48, v52, s76
	v_add3_u32 v43, v43, v50, s76
	v_add3_u32 v42, v42, v46, s76
	v_lshrrev_b32_e32 v42, 16, v42
	v_lshrrev_b32_e32 v43, 16, v43
	v_lshrrev_b32_e32 v46, 16, v48
	v_lshrrev_b32_e32 v48, 16, v49
	v_add_co_u32_e32 v86, vcc, s69, v84
	v_and_or_b32 v45, v45, s77, v48
	v_and_or_b32 v44, v44, s77, v46
	v_and_or_b32 v43, v54, s77, v43
	v_and_or_b32 v42, v56, s77, v42
	v_addc_co_u32_e32 v87, vcc, 0, v85, vcc
	v_mov_b32_e32 v50, v47
	v_mov_b32_e32 v70, v55
	global_store_dwordx4 v[86:87], v[42:45], off
	v_mov_b32_e32 v62, v59
	v_mov_b32_e32 v74, v67
	v_pk_mul_f32 v[44:45], v[50:51], v[92:93]
	v_pk_mul_f32 v[48:49], v[70:71], v[90:91]
	v_pk_mul_f32 v[42:43], v[62:63], v[76:77]
	v_pk_mul_f32 v[46:47], v[74:75], v[80:81]
	v_bfe_u32 v50, v49, 16, 1
	v_bfe_u32 v51, v48, 16, 1
	v_bfe_u32 v52, v45, 16, 1
	v_bfe_u32 v53, v44, 16, 1
	v_add3_u32 v53, v44, v53, s76
	v_add3_u32 v52, v45, v52, s76
	v_add3_u32 v44, v48, v51, s76
	v_add3_u32 v45, v49, v50, s76
	v_bfe_u32 v48, v42, 16, 1
	v_bfe_u32 v49, v43, 16, 1
	v_bfe_u32 v50, v46, 16, 1
	v_bfe_u32 v51, v47, 16, 1
	v_add3_u32 v47, v47, v51, s76
	v_add3_u32 v46, v46, v50, s76
	v_add3_u32 v43, v43, v49, s76
	v_add3_u32 v42, v42, v48, s76
	v_lshrrev_b32_e32 v42, 16, v42
	v_lshrrev_b32_e32 v43, 16, v43
	v_lshrrev_b32_e32 v46, 16, v46
	v_lshrrev_b32_e32 v47, 16, v47
	v_and_or_b32 v45, v45, s77, v47
	v_and_or_b32 v44, v44, s77, v46
	v_and_or_b32 v43, v52, s77, v43
	v_and_or_b32 v42, v53, s77, v42
	s_waitcnt vmcnt(5)
	s_waitcnt vmcnt(3)
	global_store_dwordx4 v[86:87], v[42:45], off offset:2048
	v_mul_f32_e32 v46, v40, v28
	v_mul_f32_e32 v47, v41, v36
	s_waitcnt vmcnt(3)
	v_mul_f32_e32 v42, v4, v16
	v_mul_f32_e32 v43, v5, v20
	v_mul_f32_e32 v48, v78, v24
	v_mul_f32_e32 v49, v79, v32
	v_mul_f32_e32 v44, v82, v8
	v_mul_f32_e32 v45, v83, v12
	v_bfe_u32 v24, v42, 16, 1
	v_bfe_u32 v20, v44, 16, 1
	v_bfe_u32 v28, v43, 16, 1
	v_add3_u32 v24, v42, v24, s76
	v_bfe_u32 v16, v45, 16, 1
	v_add3_u32 v20, v44, v20, s76
	v_add3_u32 v28, v43, v28, s76
	v_lshrrev_b32_e32 v24, 16, v24
	v_cvt_pk_bf16_f32 v44, v46, v48
	v_mov_b32_e32 v12, v9
	v_add3_u32 v16, v45, v16, s76
	v_lshrrev_b32_e32 v28, 16, v28
	v_cvt_pk_bf16_f32 v45, v47, v49
	v_and_or_b32 v42, v20, s77, v24
	v_mov_b32_e32 v20, v17
	v_pk_mul_f32 v[8:9], v[12:13], v[82:83]
	v_mov_b32_e32 v36, v29
	v_mov_b32_e32 v32, v25
	v_and_or_b32 v43, v16, s77, v28
	v_pk_mul_f32 v[16:17], v[20:21], v[4:5]
	v_pk_mul_f32 v[12:13], v[36:37], v[40:41]
	v_pk_mul_f32 v[20:21], v[32:33], v[78:79]
	global_store_dwordx4 v[84:85], v[42:45], off offset:32
	s_nop 1
	v_cvt_pk_bf16_f32 v45, v13, v21
	s_nop 1
	v_cvt_pk_bf16_f32 v44, v12, v20
	v_cvt_pk_bf16_f32 v43, v17, v9
	v_cvt_pk_bf16_f32 v42, v16, v8
	v_mul_f32_e32 v12, v82, v10
	v_mul_f32_e32 v13, v83, v14
	v_mul_f32_e32 v20, v78, v26
	v_mul_f32_e32 v21, v79, v34
	v_mul_f32_e32 v8, v4, v18
	v_mul_f32_e32 v9, v5, v22
	v_mul_f32_e32 v16, v40, v30
	v_mul_f32_e32 v17, v41, v38
	v_bfe_u32 v18, v8, 16, 1
	v_bfe_u32 v22, v12, 16, 1
	v_add3_u32 v8, v8, v18, s76
	v_add3_u32 v12, v12, v22, s76
	v_lshrrev_b32_e32 v8, 16, v8
	v_mov_b32_e32 v34, v27
	global_store_dwordx4 v[84:85], v[42:45], off offset:2080
	v_mov_b32_e32 v22, v19
	s_nop 1
	v_cvt_pk_bf16_f32 v44, v16, v20
	v_cvt_pk_bf16_f32 v43, v9, v13
	v_and_or_b32 v42, v12, s77, v8
	v_mov_b32_e32 v14, v11
	v_pk_mul_f32 v[12:13], v[34:35], v[78:79]
	v_pk_mul_f32 v[4:5], v[22:23], v[4:5]
	v_pk_mul_f32 v[8:9], v[14:15], v[82:83]
	v_mov_b32_e32 v38, v31
	v_cvt_pk_bf16_f32 v45, v17, v21
	v_pk_mul_f32 v[10:11], v[38:39], v[40:41]
	v_lshl_add_u64 v[6:7], v[88:89], 0, s[58:59]
	v_cvt_pk_bf16_f32 v8, v4, v8
	v_add_co_u32_e32 v4, vcc, s82, v6
	v_cvt_pk_bf16_f32 v11, v11, v13
	v_cvt_pk_bf16_f32 v10, v10, v12
	v_cvt_pk_bf16_f32 v9, v5, v9
	v_addc_co_u32_e32 v5, vcc, 0, v7, vcc
	s_mov_b32 s24, 0xa000
	global_store_dwordx4 v[86:87], v[8:11], off offset:2080
	global_store_dwordx4 v[84:85], v[94:97], off
	global_store_dwordx4 v[86:87], v[42:45], off offset:32
	v_add_co_u32_e32 v8, vcc, s24, v88
	v_mov_b32_e32 v76, 1.0
	s_nop 0
	v_addc_co_u32_e32 v9, vcc, 0, v89, vcc
	global_load_dwordx4 v[52:55], v[4:5], off nt
	global_load_dwordx4 v[44:47], v[8:9], off offset:1280 nt
	global_load_dwordx4 v[56:59], v[8:9], off offset:2560 nt
	global_load_dwordx4 v[48:51], v[8:9], off offset:3840 nt
	v_add_co_u32_e32 v4, vcc, 0xb000, v88
	v_mov_b32_e32 v92, 1.0
	s_nop 0
	v_addc_co_u32_e32 v5, vcc, 0, v89, vcc
	v_add_co_u32_e32 v8, vcc, 0xc000, v88
	global_load_dwordx4 v[64:67], v[4:5], off offset:1024 nt
	global_load_dwordx4 v[60:63], v[4:5], off offset:2304 nt
	v_addc_co_u32_e32 v9, vcc, 0, v89, vcc
	global_load_dwordx4 v[72:75], v[4:5], off offset:3584 nt
	global_load_dwordx4 v[68:71], v[8:9], off offset:768 nt
	v_mov_b32_e32 v4, 1.0
	s_and_b64 vcc, exec, s[16:17]
	v_mov_b32_e32 v77, 1.0
	v_mov_b32_e32 v93, 1.0
	v_mov_b32_e32 v80, 1.0
	v_mov_b32_e32 v90, 1.0
	v_mov_b32_e32 v81, 1.0
	v_mov_b32_e32 v91, 1.0
	s_cbranch_vccnz .LBB0_509
	global_load_dwordx4 v[76:79], v2, s[60:61] offset:128
	global_load_dwordx4 v[80:83], v2, s[60:61] offset:144
	s_waitcnt vmcnt(1)
	v_mov_b32_e32 v92, v77
	v_mov_b32_e32 v77, v78
	v_mov_b32_e32 v93, v79
	s_waitcnt vmcnt(0)
	v_mov_b32_e32 v90, v81
	v_mov_b32_e32 v81, v82
	v_mov_b32_e32 v91, v83

.LBB0_511:
	s_waitcnt vmcnt(14)
	s_waitcnt vmcnt(12)
	s_waitcnt vmcnt(11)
	s_waitcnt vmcnt(9)
	v_mul_f32_e32 v42, v92, v44
	v_mul_f32_e32 v43, v93, v48
	v_mul_f32_e32 v88, v80, v64
	v_mul_f32_e32 v89, v81, v72
	s_waitcnt vmcnt(8)
	v_mul_f32_e32 v6, v76, v52
	v_mul_f32_e32 v7, v77, v56
	v_mul_f32_e32 v94, v90, v60
	v_mul_f32_e32 v95, v91, v68
	v_bfe_u32 v48, v43, 16, 1
	v_bfe_u32 v52, v42, 16, 1
	v_add3_u32 v42, v42, v52, s76
	v_add3_u32 v43, v43, v48, s76
	v_bfe_u32 v48, v6, 16, 1
	v_bfe_u32 v52, v7, 16, 1
	v_bfe_u32 v60, v89, 16, 1
	v_add3_u32 v7, v7, v52, s76
	v_add3_u32 v6, v6, v48, s76
	v_bfe_u32 v2, v95, 16, 1
	v_add3_u32 v60, v89, v60, s76
	v_lshrrev_b32_e32 v6, 16, v6
	v_lshrrev_b32_e32 v7, 16, v7
	v_cvt_pk_bf16_f32 v96, v88, v94
	v_mov_b32_e32 v48, v45
	v_mov_b32_e32 v68, v61
	v_add3_u32 v2, v95, v2, s76
	v_lshrrev_b32_e32 v52, 16, v60
	v_and_or_b32 v95, v43, s77, v7
	v_and_or_b32 v94, v42, s77, v6
	v_mov_b32_e32 v56, v53
	v_pk_mul_f32 v[42:43], v[48:49], v[92:93]
	v_mov_b32_e32 v72, v65
	v_pk_mul_f32 v[48:49], v[68:69], v[90:91]
	v_and_or_b32 v97, v2, s77, v52
	v_pk_mul_f32 v[6:7], v[56:57], v[76:77]
	v_pk_mul_f32 v[44:45], v[72:73], v[80:81]
	v_cvt_pk_bf16_f32 v45, v45, v49
	v_cvt_pk_bf16_f32 v44, v44, v48
	v_cvt_pk_bf16_f32 v43, v7, v43
	v_cvt_pk_bf16_f32 v42, v6, v42
	global_store_dwordx4 v[84:85], v[42:45], off offset:2112
	s_nop 1
	v_mul_f32_e32 v42, v92, v46
	s_nop 1
	v_mul_f32_e32 v43, v93, v50
	v_mul_f32_e32 v48, v90, v62
	v_mul_f32_e32 v49, v91, v70
	v_mul_f32_e32 v6, v76, v54
	v_mul_f32_e32 v7, v77, v58
	v_mul_f32_e32 v44, v80, v66
	v_mul_f32_e32 v45, v81, v74
	v_cvt_pk_bf16_f32 v45, v45, v49
	v_cvt_pk_bf16_f32 v44, v44, v48
	v_cvt_pk_bf16_f32 v43, v7, v43
	v_cvt_pk_bf16_f32 v42, v6, v42
	v_mov_b32_e32 v50, v47
	v_mov_b32_e32 v70, v63
	global_store_dwordx4 v[86:87], v[42:45], off offset:64
	v_mov_b32_e32 v58, v55
	v_mov_b32_e32 v74, v67
	v_pk_mul_f32 v[42:43], v[50:51], v[92:93]
	v_pk_mul_f32 v[46:47], v[70:71], v[90:91]
	v_pk_mul_f32 v[6:7], v[58:59], v[76:77]
	v_pk_mul_f32 v[44:45], v[74:75], v[80:81]
	v_bfe_u32 v2, v47, 16, 1
	v_add3_u32 v2, v47, v2, s76
	v_bfe_u32 v50, v45, 16, 1
	v_add3_u32 v45, v45, v50, s76
	v_lshrrev_b32_e32 v45, 16, v45
	v_and_or_b32 v45, v2, s77, v45
	v_cvt_pk_bf16_f32 v44, v44, v46
	v_cvt_pk_bf16_f32 v43, v7, v43
	v_cvt_pk_bf16_f32 v42, v6, v42
	s_waitcnt vmcnt(9)
	s_waitcnt vmcnt(7)
	global_store_dwordx4 v[86:87], v[42:45], off offset:2112
	v_mul_f32_e32 v6, v4, v32
	v_mul_f32_e32 v7, v5, v36
	s_waitcnt vmcnt(5)
	s_waitcnt vmcnt(4)
	v_mul_f32_e32 v42, v82, v24
	v_mul_f32_e32 v43, v83, v28
	v_mul_f32_e32 v44, v40, v20
	v_mul_f32_e32 v45, v41, v16
	s_waitcnt vmcnt(3)
	v_bfe_u32 v24, v7, 16, 1
	v_mul_f32_e32 v46, v78, v8
	v_mul_f32_e32 v47, v79, v12
	v_bfe_u32 v12, v43, 16, 1
	v_bfe_u32 v28, v44, 16, 1
	v_add3_u32 v7, v7, v24, s76
	v_bfe_u32 v8, v46, 16, 1
	v_add3_u32 v12, v43, v12, s76
	v_add3_u32 v28, v44, v28, s76
	v_lshrrev_b32_e32 v7, 16, v7
	v_add3_u32 v8, v46, v8, s76
	v_lshrrev_b32_e32 v20, 16, v28
	v_and_or_b32 v43, v12, s77, v7
	v_mov_b32_e32 v28, v25
	v_mov_b32_e32 v12, v9
	v_cvt_pk_bf16_f32 v45, v45, v47
	v_and_or_b32 v44, v8, s77, v20
	v_cvt_pk_bf16_f32 v42, v6, v42
	v_mov_b32_e32 v36, v33
	v_pk_mul_f32 v[24:25], v[28:29], v[82:83]
	v_pk_mul_f32 v[8:9], v[12:13], v[78:79]
	v_pk_mul_f32 v[6:7], v[36:37], v[4:5]
	v_mul_f32_e32 v16, v40, v21
	v_mul_f32_e32 v17, v41, v17
	v_bfe_u32 v2, v9, 16, 1
	v_bfe_u32 v20, v24, 16, 1
	v_add3_u32 v20, v24, v20, s76
	v_add3_u32 v2, v9, v2, s76
	v_bfe_u32 v9, v6, 16, 1
	v_bfe_u32 v24, v17, 16, 1
	v_add3_u32 v17, v17, v24, s76
	v_add3_u32 v6, v6, v9, s76
	v_lshrrev_b32_e32 v6, 16, v6
	v_lshrrev_b32_e32 v9, 16, v17
	v_and_or_b32 v9, v2, s77, v9
	v_cvt_pk_bf16_f32 v8, v16, v8
	v_cvt_pk_bf16_f32 v7, v7, v25
	v_and_or_b32 v6, v20, s77, v6
	global_store_dwordx4 v[84:85], v[6:9], off offset:2144
	s_nop 1
	v_mul_f32_e32 v8, v82, v26
	s_nop 1
	v_mul_f32_e32 v9, v83, v30
	v_mul_f32_e32 v16, v78, v10
	v_mul_f32_e32 v17, v79, v14
	v_mul_f32_e32 v6, v4, v34
	v_mul_f32_e32 v7, v5, v38
	v_mul_f32_e32 v12, v40, v22
	v_mul_f32_e32 v13, v41, v18
	v_bfe_u32 v14, v9, 16, 1
	v_bfe_u32 v18, v8, 16, 1
	v_add3_u32 v18, v8, v18, s76
	v_add3_u32 v14, v9, v14, s76
	v_bfe_u32 v9, v6, 16, 1
	v_bfe_u32 v10, v7, 16, 1
	v_add3_u32 v7, v7, v10, s76
	v_add3_u32 v6, v6, v9, s76
	v_lshrrev_b32_e32 v6, 16, v6
	v_lshrrev_b32_e32 v7, 16, v7
	v_mov_b32_e32 v38, v35
	v_cvt_pk_bf16_f32 v9, v13, v17
	v_cvt_pk_bf16_f32 v8, v12, v16
	v_and_or_b32 v7, v14, s77, v7
	v_and_or_b32 v6, v18, s77, v6
	v_pk_mul_f32 v[4:5], v[38:39], v[4:5]
	v_mov_b32_e32 v30, v27
	global_store_dwordx4 v[86:87], v[6:9], off offset:96
	v_and_b32_sdwa v2, v5, v171 dst_sel:DWORD dst_unused:UNUSED_PAD src0_sel:WORD_1 src1_sel:DWORD
	v_add3_u32 v2, v5, v2, s76
	v_pk_mul_f32 v[6:7], v[30:31], v[82:83]
	v_and_b32_sdwa v8, v4, v171 dst_sel:DWORD dst_unused:UNUSED_PAD src0_sel:WORD_1 src1_sel:DWORD
	v_add3_u32 v4, v4, v8, s76
	v_and_b32_sdwa v8, v6, v171 dst_sel:DWORD dst_unused:UNUSED_PAD src0_sel:WORD_1 src1_sel:DWORD
	v_add3_u32 v6, v6, v8, s76
	v_and_b32_sdwa v5, v7, v171 dst_sel:DWORD dst_unused:UNUSED_PAD src0_sel:WORD_1 src1_sel:DWORD
	v_and_b32_e32 v6, 0xffff0000, v6
	v_add3_u32 v5, v7, v5, s76
	v_or_b32_sdwa v4, v6, v4 dst_sel:DWORD dst_unused:UNUSED_PAD src0_sel:DWORD src1_sel:WORD_1
	v_mov_b32_e32 v10, v23
	v_mov_b32_e32 v6, v40
	v_mov_b32_e32 v7, v78
	v_pk_mul_f32 v[6:7], v[10:11], v[6:7]
	v_and_b32_e32 v5, 0xffff0000, v5
	v_and_b32_sdwa v8, v6, v171 dst_sel:DWORD dst_unused:UNUSED_PAD src0_sel:WORD_1 src1_sel:DWORD
	v_mov_b32_e32 v14, v19
	v_mov_b32_e32 v78, v41
	v_or_b32_sdwa v5, v5, v2 dst_sel:DWORD dst_unused:UNUSED_PAD src0_sel:DWORD src1_sel:WORD_1
	v_and_b32_sdwa v2, v7, v171 dst_sel:DWORD dst_unused:UNUSED_PAD src0_sel:WORD_1 src1_sel:DWORD
	v_add3_u32 v6, v6, v8, s76
	v_pk_mul_f32 v[8:9], v[14:15], v[78:79]
	v_add3_u32 v2, v7, v2, s76
	v_lshrrev_b32_e32 v6, 16, v6
	v_and_b32_sdwa v7, v8, v171 dst_sel:DWORD dst_unused:UNUSED_PAD src0_sel:WORD_1 src1_sel:DWORD
	v_and_or_b32 v6, v2, s77, v6
	v_and_b32_sdwa v2, v9, v171 dst_sel:DWORD dst_unused:UNUSED_PAD src0_sel:WORD_1 src1_sel:DWORD
	v_add3_u32 v7, v8, v7, s76
	v_add3_u32 v2, v9, v2, s76
	v_lshrrev_b32_e32 v7, 16, v7
	v_and_or_b32 v7, v2, s77, v7
	global_store_dwordx4 v[84:85], v[94:97], off offset:64
	global_store_dwordx4 v[84:85], v[42:45], off offset:96

.LBB0_516:
	s_andn2_b64 vcc, exec, s[16:17]
	s_cbranch_vccnz .LBB0_518
	s_mov_b64 s[16:17], s[0:1]
	s_mov_b64 s[26:27], s[0:1]
	s_load_dwordx2 s[16:17], s[16:17], 0x90
	s_lshl_b32 s24, s23, 3
	s_load_dwordx2 s[26:27], s[26:27], 0xa8
	s_addk_i32 s24, 0x100
	s_and_b32 s60, s24, 0x7c0
	s_lshl_b32 s24, s23, 7
	s_and_b32 s24, s24, 0x380
	v_or_b32_e32 v6, s24, v155
	v_lshlrev_b32_e32 v2, 11, v6
	s_waitcnt lgkmcnt(0)
	v_lshl_add_u64 v[4:5], s[26:27], 0, v[2:3]
	s_lshl_b32 s24, s60, 1
	v_lshl_add_u64 v[4:5], v[4:5], 0, s[24:25]
	v_lshlrev_b32_e32 v2, 1, v116
	v_lshl_add_u64 v[70:71], v[4:5], 0, v[2:3]
	v_or_b32_e32 v7, s60, v116
	v_lshlrev_b32_e32 v2, 2, v6
	v_lshl_add_u64 v[4:5], s[16:17], 0, v[2:3]
	v_lshlrev_b32_e32 v2, 12, v7
	v_lshl_add_u64 v[72:73], v[4:5], 0, v[2:3]
	v_add_co_u32_e32 v4, vcc, s81, v72
	global_load_dwordx4 v[36:39], v[72:73], off nt
	s_nop 0
	v_addc_co_u32_e32 v5, vcc, 0, v73, vcc
	global_load_dwordx4 v[52:55], v[4:5], off offset:-4096 nt
	global_load_dwordx4 v[40:43], v[4:5], off nt
	v_add_co_u32_e32 v4, vcc, s70, v72
	s_mov_b64 s[16:17], 0x53c0000
	s_nop 0
	v_addc_co_u32_e32 v5, vcc, 0, v73, vcc
	global_load_dwordx4 v[56:59], v[4:5], off offset:-4096 nt
	global_load_dwordx4 v[44:47], v[4:5], off nt
	v_add_co_u32_e32 v4, vcc, s72, v72
	v_lshl_add_u64 v[68:69], v[70:71], 0, s[16:17]
	s_nop 0
	v_addc_co_u32_e32 v5, vcc, 0, v73, vcc
	global_load_dwordx4 v[60:63], v[4:5], off offset:-4096 nt
	global_load_dwordx4 v[48:51], v[4:5], off nt
	v_add_co_u32_e32 v4, vcc, s73, v72
	s_mov_b32 s16, 0x53c1000
	s_nop 0
	v_addc_co_u32_e32 v5, vcc, 0, v73, vcc
	global_load_dwordx4 v[64:67], v[4:5], off nt
	v_add_co_u32_e32 v4, vcc, s83, v72
	s_waitcnt vmcnt(7)
	v_bfe_u32 v2, v36, 16, 1
	v_addc_co_u32_e32 v5, vcc, 0, v73, vcc
	v_add_co_u32_e32 v6, vcc, s86, v72
	v_add3_u32 v2, v36, v2, s76
	s_nop 0
	v_addc_co_u32_e32 v7, vcc, 0, v73, vcc
	v_add_co_u32_e32 v12, vcc, s87, v72
	s_waitcnt vmcnt(6)
	v_bfe_u32 v36, v52, 16, 1
	v_addc_co_u32_e32 v13, vcc, 0, v73, vcc
	v_add_co_u32_e32 v14, vcc, s88, v72
	s_waitcnt vmcnt(5)
	v_bfe_u32 v74, v40, 16, 1
	v_addc_co_u32_e32 v15, vcc, 0, v73, vcc
	global_load_dwordx4 v[32:35], v[4:5], off offset:-4096 nt
	global_load_dwordx4 v[28:31], v[4:5], off nt
	global_load_dwordx4 v[24:27], v[6:7], off offset:-4096 nt
	global_load_dwordx4 v[16:19], v[6:7], off nt
	global_load_dwordx4 v[8:11], v[12:13], off offset:-4096 nt
	s_nop 0
	global_load_dwordx4 v[4:7], v[12:13], off nt
	global_load_dwordx4 v[20:23], v[14:15], off offset:-4096 nt
	s_nop 0
	global_load_dwordx4 v[12:15], v[14:15], off nt
	s_waitcnt vmcnt(12)
	v_bfe_u32 v75, v56, 16, 1
	s_waitcnt vmcnt(11)
	v_lshrrev_b32_e32 v2, 16, v2
	v_add3_u32 v36, v52, v36, s76
	v_add3_u32 v40, v40, v74, s76
	s_waitcnt vmcnt(10)
	s_waitcnt vmcnt(9)
	v_add3_u32 v52, v56, v75, s76
	v_and_or_b32 v74, v36, s77, v2
	v_lshrrev_b32_e32 v2, 16, v40
	s_waitcnt vmcnt(8)
	v_and_or_b32 v75, v52, s77, v2
	v_bfe_u32 v2, v37, 16, 1
	v_cvt_pk_bf16_f32 v76, v44, v60
	v_add_co_u32_e32 v70, vcc, s16, v70
	v_add3_u32 v2, v37, v2, s76
	v_bfe_u32 v36, v53, 16, 1
	v_cvt_pk_bf16_f32 v77, v48, v64
	v_addc_co_u32_e32 v71, vcc, 0, v71, vcc
	v_lshrrev_b32_e32 v2, 16, v2
	v_add3_u32 v36, v53, v36, s76
	global_store_dwordx4 v[70:71], v[74:77], off offset:-4096
	s_nop 1
	v_and_or_b32 v74, v36, s77, v2
	s_nop 1
	v_cvt_pk_bf16_f32 v75, v41, v57
	v_cvt_pk_bf16_f32 v76, v45, v61
	v_cvt_pk_bf16_f32 v77, v49, v65
	v_bfe_u32 v2, v38, 16, 1
	v_add3_u32 v2, v38, v2, s76
	v_bfe_u32 v36, v54, 16, 1
	v_lshrrev_b32_e32 v2, 16, v2
	v_add3_u32 v36, v54, v36, s76
	global_store_dwordx4 v[68:69], v[74:77], off offset:2048
	s_nop 1
	v_and_or_b32 v74, v36, s77, v2
	s_nop 1
	v_cvt_pk_bf16_f32 v75, v42, v58
	v_cvt_pk_bf16_f32 v76, v46, v62
	v_cvt_pk_bf16_f32 v77, v50, v66
	v_cvt_pk_bf16_f32 v36, v39, v55
	v_cvt_pk_bf16_f32 v37, v43, v59
	v_cvt_pk_bf16_f32 v38, v47, v63
	v_cvt_pk_bf16_f32 v39, v51, v67
	s_waitcnt vmcnt(9)
	s_waitcnt vmcnt(8)
	global_store_dwordx4 v[70:71], v[36:39], off offset:2048
	global_store_dwordx4 v[70:71], v[74:77], off
	s_nop 0
	v_cvt_pk_bf16_f32 v36, v32, v28
	s_waitcnt vmcnt(9)
	s_waitcnt vmcnt(8)
	v_cvt_pk_bf16_f32 v37, v24, v16
	s_waitcnt vmcnt(7)
	s_waitcnt vmcnt(6)
	v_cvt_pk_bf16_f32 v38, v8, v4
	s_waitcnt vmcnt(5)
	s_waitcnt vmcnt(4)
	v_cvt_pk_bf16_f32 v39, v20, v12
	global_store_dwordx4 v[68:69], v[36:39], off offset:32
	v_add_co_u32_e32 v8, vcc, s75, v72
	s_nop 0
	v_cvt_pk_bf16_f32 v36, v33, v29
	v_cvt_pk_bf16_f32 v37, v25, v17
	v_cvt_pk_bf16_f32 v38, v9, v5
	v_cvt_pk_bf16_f32 v39, v21, v13
	global_store_dwordx4 v[68:69], v[36:39], off offset:2080
	s_nop 1
	v_cvt_pk_bf16_f32 v36, v34, v30
	s_nop 1
	v_cvt_pk_bf16_f32 v37, v26, v18
	v_cvt_pk_bf16_f32 v38, v10, v6
	v_cvt_pk_bf16_f32 v39, v22, v14
	v_cvt_pk_bf16_f32 v4, v35, v31
	v_cvt_pk_bf16_f32 v5, v27, v19
	v_cvt_pk_bf16_f32 v6, v11, v7
	v_cvt_pk_bf16_f32 v7, v23, v15
	global_store_dwordx4 v[70:71], v[36:39], off offset:32
	global_store_dwordx4 v[70:71], v[4:7], off offset:2080
	v_addc_co_u32_e32 v9, vcc, 0, v73, vcc
	global_load_dwordx4 v[4:7], v[8:9], off offset:-4096 nt
	s_nop 0
	global_load_dwordx4 v[8:11], v[8:9], off nt
	v_add_co_u32_e32 v16, vcc, s89, v72
	s_waitcnt vmcnt(1)
	v_addc_co_u32_e32 v17, vcc, 0, v73, vcc
	global_load_dwordx4 v[12:15], v[16:17], off offset:-4096 nt
	s_nop 0
	global_load_dwordx4 v[16:19], v[16:17], off nt
	v_add_co_u32_e32 v24, vcc, s84, v72
	s_nop 0
	v_addc_co_u32_e32 v25, vcc, 0, v73, vcc
	global_load_dwordx4 v[20:23], v[24:25], off offset:-4096 nt
	s_nop 0
	global_load_dwordx4 v[24:27], v[24:25], off nt
	v_add_co_u32_e32 v32, vcc, s85, v72
	s_waitcnt vmcnt(4)
	v_addc_co_u32_e32 v33, vcc, 0, v73, vcc
	global_load_dwordx4 v[28:31], v[32:33], off offset:-4096 nt
	s_nop 0
	global_load_dwordx4 v[32:35], v[32:33], off nt
	v_add_co_u32_e32 v40, vcc, s78, v72
	s_nop 0
	v_addc_co_u32_e32 v41, vcc, 0, v73, vcc
	global_load_dwordx4 v[36:39], v[40:41], off offset:-4096 nt
	s_nop 0
	global_load_dwordx4 v[40:43], v[40:41], off nt
	v_add_co_u32_e32 v48, vcc, s79, v72
	s_nop 0
	v_addc_co_u32_e32 v49, vcc, 0, v73, vcc
	global_load_dwordx4 v[44:47], v[48:49], off offset:-4096 nt
	s_nop 0
	global_load_dwordx4 v[48:51], v[48:49], off nt
	v_add_co_u32_e32 v56, vcc, s90, v72
	s_nop 1
	v_addc_co_u32_e32 v57, vcc, 0, v73, vcc
	global_load_dwordx4 v[52:55], v[56:57], off offset:-4096 nt
	s_nop 0
	global_load_dwordx4 v[56:59], v[56:57], off nt
	v_add_co_u32_e32 v64, vcc, s80, v72
	v_cvt_pk_bf16_f32 v72, v4, v8
	s_nop 0
	v_addc_co_u32_e32 v65, vcc, 0, v73, vcc
	global_load_dwordx4 v[60:63], v[64:65], off offset:-4096 nt
	s_nop 0
	global_load_dwordx4 v[64:67], v[64:65], off nt
	s_waitcnt vmcnt(13)
	s_waitcnt vmcnt(12)
	v_cvt_pk_bf16_f32 v73, v12, v16
	s_waitcnt vmcnt(11)
	s_waitcnt vmcnt(10)
	v_cvt_pk_bf16_f32 v74, v20, v24
	s_waitcnt vmcnt(9)
	s_waitcnt vmcnt(8)
	v_cvt_pk_bf16_f32 v75, v28, v32
	v_bfe_u32 v2, v5, 16, 1
	v_add3_u32 v2, v5, v2, s76
	v_bfe_u32 v4, v9, 16, 1
	v_lshrrev_b32_e32 v2, 16, v2
	v_add3_u32 v4, v9, v4, s76
	global_store_dwordx4 v[68:69], v[72:75], off offset:64
	s_nop 1
	v_and_or_b32 v72, v4, s77, v2
	s_nop 1
	v_cvt_pk_bf16_f32 v73, v13, v17
	v_cvt_pk_bf16_f32 v74, v21, v25
	v_cvt_pk_bf16_f32 v75, v29, v33
	v_bfe_u32 v2, v6, 16, 1
	v_add3_u32 v2, v6, v2, s76
	v_bfe_u32 v4, v10, 16, 1
	v_lshrrev_b32_e32 v2, 16, v2
	v_add3_u32 v4, v10, v4, s76
	global_store_dwordx4 v[68:69], v[72:75], off offset:2112
	s_nop 1
	v_and_or_b32 v72, v4, s77, v2
	s_nop 1
	v_cvt_pk_bf16_f32 v73, v14, v18
	v_cvt_pk_bf16_f32 v74, v22, v26
	v_cvt_pk_bf16_f32 v75, v30, v34
	v_cvt_pk_bf16_f32 v4, v7, v11
	v_cvt_pk_bf16_f32 v5, v15, v19
	v_cvt_pk_bf16_f32 v6, v23, v27
	v_cvt_pk_bf16_f32 v7, v31, v35
	s_waitcnt vmcnt(9)
	global_store_dwordx4 v[70:71], v[4:7], off offset:2112
	s_waitcnt vmcnt(9)
	s_nop 1
	v_cvt_pk_bf16_f32 v4, v36, v40
	s_waitcnt vmcnt(8)
	s_waitcnt vmcnt(7)
	v_cvt_pk_bf16_f32 v5, v44, v48
	s_waitcnt vmcnt(6)
	s_waitcnt vmcnt(5)
	v_cvt_pk_bf16_f32 v6, v52, v56
	s_waitcnt vmcnt(4)
	s_waitcnt vmcnt(3)
	v_cvt_pk_bf16_f32 v7, v60, v64
	global_store_dwordx4 v[68:69], v[4:7], off offset:96
	s_nop 1
	v_cvt_pk_bf16_f32 v4, v37, v41
	s_nop 1
	v_cvt_pk_bf16_f32 v5, v45, v49
	v_cvt_pk_bf16_f32 v6, v53, v57
	v_cvt_pk_bf16_f32 v7, v61, v65
	global_store_dwordx4 v[68:69], v[4:7], off offset:2144
	s_nop 1
	v_cvt_pk_bf16_f32 v4, v38, v42
	s_nop 1
	v_cvt_pk_bf16_f32 v5, v46, v50
	v_cvt_pk_bf16_f32 v6, v54, v58
	v_cvt_pk_bf16_f32 v7, v62, v66
	global_store_dwordx4 v[70:71], v[4:7], off offset:96
	s_nop 1
	v_cvt_pk_bf16_f32 v4, v39, v43
	s_nop 1
	v_cvt_pk_bf16_f32 v5, v47, v51
	v_cvt_pk_bf16_f32 v6, v55, v59
	v_cvt_pk_bf16_f32 v7, v63, v67
	global_store_dwordx4 v[70:71], v[72:75], off offset:64
	global_store_dwordx4 v[70:71], v[4:7], off offset:2144

.LBB0_519:
	s_andn2_b64 vcc, exec, s[16:17]
	s_cbranch_vccnz .LBB0_521
	s_mov_b64 s[16:17], s[0:1]
	s_mov_b64 s[26:27], s[0:1]
	s_load_dwordx2 s[16:17], s[16:17], 0x50
	s_lshl_b32 s24, s23, 3
	s_load_dwordx2 s[26:27], s[26:27], 0xa8
	s_addk_i32 s24, 0x500
	s_and_b32 s60, s24, 0x7c0
	s_lshl_b32 s24, s23, 7
	s_and_b32 s24, s24, 0x380
	v_or_b32_e32 v6, s24, v155
	v_lshlrev_b32_e32 v2, 11, v6
	s_waitcnt lgkmcnt(0)
	v_lshl_add_u64 v[4:5], s[26:27], 0, v[2:3]
	s_lshl_b32 s24, s60, 1
	v_lshl_add_u64 v[4:5], v[4:5], 0, s[24:25]
	v_lshlrev_b32_e32 v2, 1, v116
	v_lshl_add_u64 v[70:71], v[4:5], 0, v[2:3]
	v_or_b32_e32 v7, s60, v116
	v_lshlrev_b32_e32 v2, 2, v6
	v_lshl_add_u64 v[4:5], s[16:17], 0, v[2:3]
	v_lshlrev_b32_e32 v2, 12, v7
	v_lshl_add_u64 v[72:73], v[4:5], 0, v[2:3]
	v_add_co_u32_e32 v4, vcc, s81, v72
	global_load_dwordx4 v[36:39], v[72:73], off nt
	s_nop 0
	v_addc_co_u32_e32 v5, vcc, 0, v73, vcc
	global_load_dwordx4 v[52:55], v[4:5], off offset:-4096 nt
	global_load_dwordx4 v[40:43], v[4:5], off nt
	v_add_co_u32_e32 v4, vcc, s70, v72
	s_mov_b64 s[16:17], 0x4c00000
	s_nop 0
	v_addc_co_u32_e32 v5, vcc, 0, v73, vcc
	global_load_dwordx4 v[56:59], v[4:5], off offset:-4096 nt
	global_load_dwordx4 v[44:47], v[4:5], off nt
	v_add_co_u32_e32 v4, vcc, s72, v72
	v_lshl_add_u64 v[68:69], v[70:71], 0, s[16:17]
	s_nop 0
	v_addc_co_u32_e32 v5, vcc, 0, v73, vcc
	global_load_dwordx4 v[60:63], v[4:5], off offset:-4096 nt
	global_load_dwordx4 v[48:51], v[4:5], off nt
	v_add_co_u32_e32 v4, vcc, s73, v72
	s_mov_b32 s16, 0x4c01000
	s_nop 0
	v_addc_co_u32_e32 v5, vcc, 0, v73, vcc
	global_load_dwordx4 v[64:67], v[4:5], off nt
	v_add_co_u32_e32 v4, vcc, s83, v72
	s_waitcnt vmcnt(7)
	v_bfe_u32 v2, v36, 16, 1
	v_addc_co_u32_e32 v5, vcc, 0, v73, vcc
	v_add_co_u32_e32 v6, vcc, s86, v72
	v_add3_u32 v2, v36, v2, s76
	s_nop 0
	v_addc_co_u32_e32 v7, vcc, 0, v73, vcc
	v_add_co_u32_e32 v12, vcc, s87, v72
	s_waitcnt vmcnt(6)
	v_bfe_u32 v36, v52, 16, 1
	v_addc_co_u32_e32 v13, vcc, 0, v73, vcc
	v_add_co_u32_e32 v14, vcc, s88, v72
	s_waitcnt vmcnt(5)
	v_bfe_u32 v74, v40, 16, 1
	v_addc_co_u32_e32 v15, vcc, 0, v73, vcc
	global_load_dwordx4 v[32:35], v[4:5], off offset:-4096 nt
	global_load_dwordx4 v[28:31], v[4:5], off nt
	global_load_dwordx4 v[24:27], v[6:7], off offset:-4096 nt
	global_load_dwordx4 v[16:19], v[6:7], off nt
	global_load_dwordx4 v[8:11], v[12:13], off offset:-4096 nt
	s_nop 0
	global_load_dwordx4 v[4:7], v[12:13], off nt
	global_load_dwordx4 v[20:23], v[14:15], off offset:-4096 nt
	s_nop 0
	global_load_dwordx4 v[12:15], v[14:15], off nt
	s_waitcnt vmcnt(12)
	v_bfe_u32 v75, v56, 16, 1
	s_waitcnt vmcnt(11)
	v_lshrrev_b32_e32 v2, 16, v2
	v_add3_u32 v36, v52, v36, s76
	v_add3_u32 v40, v40, v74, s76
	s_waitcnt vmcnt(10)
	s_waitcnt vmcnt(9)
	v_add3_u32 v52, v56, v75, s76
	v_and_or_b32 v74, v36, s77, v2
	v_lshrrev_b32_e32 v2, 16, v40
	s_waitcnt vmcnt(8)
	v_and_or_b32 v75, v52, s77, v2
	v_bfe_u32 v2, v37, 16, 1
	v_cvt_pk_bf16_f32 v76, v44, v60
	v_add_co_u32_e32 v70, vcc, s16, v70
	v_add3_u32 v2, v37, v2, s76
	v_bfe_u32 v36, v53, 16, 1
	v_cvt_pk_bf16_f32 v77, v48, v64
	v_addc_co_u32_e32 v71, vcc, 0, v71, vcc
	v_lshrrev_b32_e32 v2, 16, v2
	v_add3_u32 v36, v53, v36, s76
	global_store_dwordx4 v[70:71], v[74:77], off offset:-4096
	s_nop 1
	v_and_or_b32 v74, v36, s77, v2
	s_nop 1
	v_cvt_pk_bf16_f32 v75, v41, v57
	v_cvt_pk_bf16_f32 v76, v45, v61
	v_cvt_pk_bf16_f32 v77, v49, v65
	v_bfe_u32 v2, v38, 16, 1
	v_add3_u32 v2, v38, v2, s76
	v_bfe_u32 v36, v54, 16, 1
	v_lshrrev_b32_e32 v2, 16, v2
	v_add3_u32 v36, v54, v36, s76
	global_store_dwordx4 v[68:69], v[74:77], off offset:2048
	s_nop 1
	v_and_or_b32 v74, v36, s77, v2
	s_nop 1
	v_cvt_pk_bf16_f32 v75, v42, v58
	v_cvt_pk_bf16_f32 v76, v46, v62
	v_cvt_pk_bf16_f32 v77, v50, v66
	v_cvt_pk_bf16_f32 v36, v39, v55
	v_cvt_pk_bf16_f32 v37, v43, v59
	v_cvt_pk_bf16_f32 v38, v47, v63
	v_cvt_pk_bf16_f32 v39, v51, v67
	s_waitcnt vmcnt(9)
	s_waitcnt vmcnt(8)
	global_store_dwordx4 v[70:71], v[36:39], off offset:2048
	global_store_dwordx4 v[70:71], v[74:77], off
	s_nop 0
	v_cvt_pk_bf16_f32 v36, v32, v28
	s_waitcnt vmcnt(9)
	s_waitcnt vmcnt(8)
	v_cvt_pk_bf16_f32 v37, v24, v16
	s_waitcnt vmcnt(7)
	s_waitcnt vmcnt(6)
	v_cvt_pk_bf16_f32 v38, v8, v4
	s_waitcnt vmcnt(5)
	s_waitcnt vmcnt(4)
	v_cvt_pk_bf16_f32 v39, v20, v12
	global_store_dwordx4 v[68:69], v[36:39], off offset:32
	v_add_co_u32_e32 v8, vcc, s75, v72
	s_nop 0
	v_cvt_pk_bf16_f32 v36, v33, v29
	v_cvt_pk_bf16_f32 v37, v25, v17
	v_cvt_pk_bf16_f32 v38, v9, v5
	v_cvt_pk_bf16_f32 v39, v21, v13
	global_store_dwordx4 v[68:69], v[36:39], off offset:2080
	s_nop 1
	v_cvt_pk_bf16_f32 v36, v34, v30
	s_nop 1
	v_cvt_pk_bf16_f32 v37, v26, v18
	v_cvt_pk_bf16_f32 v38, v10, v6
	v_cvt_pk_bf16_f32 v39, v22, v14
	v_cvt_pk_bf16_f32 v4, v35, v31
	v_cvt_pk_bf16_f32 v5, v27, v19
	v_cvt_pk_bf16_f32 v6, v11, v7
	v_cvt_pk_bf16_f32 v7, v23, v15
	global_store_dwordx4 v[70:71], v[36:39], off offset:32
	global_store_dwordx4 v[70:71], v[4:7], off offset:2080
	v_addc_co_u32_e32 v9, vcc, 0, v73, vcc
	global_load_dwordx4 v[4:7], v[8:9], off offset:-4096 nt
	s_nop 0
	global_load_dwordx4 v[8:11], v[8:9], off nt
	v_add_co_u32_e32 v16, vcc, s89, v72
	s_waitcnt vmcnt(1)
	v_addc_co_u32_e32 v17, vcc, 0, v73, vcc
	global_load_dwordx4 v[12:15], v[16:17], off offset:-4096 nt
	s_nop 0
	global_load_dwordx4 v[16:19], v[16:17], off nt
	v_add_co_u32_e32 v24, vcc, s84, v72
	s_nop 0
	v_addc_co_u32_e32 v25, vcc, 0, v73, vcc
	global_load_dwordx4 v[20:23], v[24:25], off offset:-4096 nt
	s_nop 0
	global_load_dwordx4 v[24:27], v[24:25], off nt
	v_add_co_u32_e32 v32, vcc, s85, v72
	s_waitcnt vmcnt(4)
	v_addc_co_u32_e32 v33, vcc, 0, v73, vcc
	global_load_dwordx4 v[28:31], v[32:33], off offset:-4096 nt
	s_nop 0
	global_load_dwordx4 v[32:35], v[32:33], off nt
	v_add_co_u32_e32 v40, vcc, s78, v72
	s_nop 0
	v_addc_co_u32_e32 v41, vcc, 0, v73, vcc
	global_load_dwordx4 v[36:39], v[40:41], off offset:-4096 nt
	s_nop 0
	global_load_dwordx4 v[40:43], v[40:41], off nt
	v_add_co_u32_e32 v48, vcc, s79, v72
	s_nop 0
	v_addc_co_u32_e32 v49, vcc, 0, v73, vcc
	global_load_dwordx4 v[44:47], v[48:49], off offset:-4096 nt
	s_nop 0
	global_load_dwordx4 v[48:51], v[48:49], off nt
	v_add_co_u32_e32 v56, vcc, s90, v72
	s_nop 1
	v_addc_co_u32_e32 v57, vcc, 0, v73, vcc
	global_load_dwordx4 v[52:55], v[56:57], off offset:-4096 nt
	s_nop 0
	global_load_dwordx4 v[56:59], v[56:57], off nt
	v_add_co_u32_e32 v64, vcc, s80, v72
	v_cvt_pk_bf16_f32 v72, v4, v8
	s_nop 0
	v_addc_co_u32_e32 v65, vcc, 0, v73, vcc
	global_load_dwordx4 v[60:63], v[64:65], off offset:-4096 nt
	s_nop 0
	global_load_dwordx4 v[64:67], v[64:65], off nt
	s_waitcnt vmcnt(13)
	s_waitcnt vmcnt(12)
	v_cvt_pk_bf16_f32 v73, v12, v16
	s_waitcnt vmcnt(11)
	s_waitcnt vmcnt(10)
	v_cvt_pk_bf16_f32 v74, v20, v24
	s_waitcnt vmcnt(9)
	s_waitcnt vmcnt(8)
	v_cvt_pk_bf16_f32 v75, v28, v32
	v_bfe_u32 v2, v5, 16, 1
	v_add3_u32 v2, v5, v2, s76
	v_bfe_u32 v4, v9, 16, 1
	v_lshrrev_b32_e32 v2, 16, v2
	v_add3_u32 v4, v9, v4, s76
	global_store_dwordx4 v[68:69], v[72:75], off offset:64
	s_nop 1
	v_and_or_b32 v72, v4, s77, v2
	s_nop 1
	v_cvt_pk_bf16_f32 v73, v13, v17
	v_cvt_pk_bf16_f32 v74, v21, v25
	v_cvt_pk_bf16_f32 v75, v29, v33
	v_bfe_u32 v2, v6, 16, 1
	v_add3_u32 v2, v6, v2, s76
	v_bfe_u32 v4, v10, 16, 1
	v_lshrrev_b32_e32 v2, 16, v2
	v_add3_u32 v4, v10, v4, s76
	global_store_dwordx4 v[68:69], v[72:75], off offset:2112
	s_nop 1
	v_and_or_b32 v72, v4, s77, v2
	s_nop 1
	v_cvt_pk_bf16_f32 v73, v14, v18
	v_cvt_pk_bf16_f32 v74, v22, v26
	v_cvt_pk_bf16_f32 v75, v30, v34
	v_cvt_pk_bf16_f32 v4, v7, v11
	v_cvt_pk_bf16_f32 v5, v15, v19
	v_cvt_pk_bf16_f32 v6, v23, v27
	v_cvt_pk_bf16_f32 v7, v31, v35
	s_waitcnt vmcnt(9)
	global_store_dwordx4 v[70:71], v[4:7], off offset:2112
	s_waitcnt vmcnt(9)
	s_nop 1
	v_cvt_pk_bf16_f32 v4, v36, v40
	s_waitcnt vmcnt(8)
	s_waitcnt vmcnt(7)
	v_cvt_pk_bf16_f32 v5, v44, v48
	s_waitcnt vmcnt(6)
	s_waitcnt vmcnt(5)
	v_cvt_pk_bf16_f32 v6, v52, v56
	s_waitcnt vmcnt(4)
	s_waitcnt vmcnt(3)
	v_cvt_pk_bf16_f32 v7, v60, v64
	global_store_dwordx4 v[68:69], v[4:7], off offset:96
	s_nop 1
	v_cvt_pk_bf16_f32 v4, v37, v41
	s_nop 1
	v_cvt_pk_bf16_f32 v5, v45, v49
	v_cvt_pk_bf16_f32 v6, v53, v57
	v_cvt_pk_bf16_f32 v7, v61, v65
	global_store_dwordx4 v[68:69], v[4:7], off offset:2144
	s_nop 1
	v_cvt_pk_bf16_f32 v4, v38, v42
	s_nop 1
	v_cvt_pk_bf16_f32 v5, v46, v50
	v_cvt_pk_bf16_f32 v6, v54, v58
	v_cvt_pk_bf16_f32 v7, v62, v66
	global_store_dwordx4 v[70:71], v[4:7], off offset:96
	s_nop 1
	v_cvt_pk_bf16_f32 v4, v39, v43
	s_nop 1
	v_cvt_pk_bf16_f32 v5, v47, v51
	v_cvt_pk_bf16_f32 v6, v55, v59
	v_cvt_pk_bf16_f32 v7, v63, v67
	global_store_dwordx4 v[70:71], v[72:75], off offset:64
	global_store_dwordx4 v[70:71], v[4:7], off offset:2144

.LBB0_550:
	s_waitcnt vmcnt(14)
	s_waitcnt vmcnt(12)
	s_waitcnt vmcnt(11)
	s_waitcnt vmcnt(9)
	v_mul_f32_e32 v34, v96, v44
	v_mul_f32_e32 v35, v97, v52
	v_mul_f32_e32 v88, v80, v64
	v_mul_f32_e32 v89, v81, v72
	s_waitcnt vmcnt(8)
	v_mul_f32_e32 v6, v76, v48
	v_mul_f32_e32 v7, v77, v60
	v_mul_f32_e32 v90, v94, v56
	v_mul_f32_e32 v91, v95, v68
	v_bfe_u32 v48, v35, 16, 1
	v_bfe_u32 v52, v34, 16, 1
	v_add3_u32 v34, v34, v52, s76
	v_add3_u32 v35, v35, v48, s76
	v_bfe_u32 v48, v6, 16, 1
	v_bfe_u32 v52, v7, 16, 1
	v_add3_u32 v7, v7, v52, s76
	v_add3_u32 v6, v6, v48, s76
	v_lshrrev_b32_e32 v6, 16, v6
	v_lshrrev_b32_e32 v7, 16, v7
	v_cvt_pk_bf16_f32 v91, v89, v91
	v_mov_b32_e32 v52, v45
	v_mov_b32_e32 v68, v57
	v_cvt_pk_bf16_f32 v90, v88, v90
	v_and_or_b32 v89, v35, s77, v7
	v_and_or_b32 v88, v34, s77, v6
	v_mov_b32_e32 v60, v49
	v_pk_mul_f32 v[34:35], v[52:53], v[96:97]
	v_mov_b32_e32 v72, v65
	v_pk_mul_f32 v[48:49], v[68:69], v[94:95]
	v_pk_mul_f32 v[6:7], v[60:61], v[76:77]
	v_pk_mul_f32 v[44:45], v[72:73], v[80:81]
	v_bfe_u32 v2, v49, 16, 1
	v_bfe_u32 v56, v34, 16, 1
	v_add3_u32 v2, v49, v2, s76
	v_bfe_u32 v49, v6, 16, 1
	v_add3_u32 v34, v34, v56, s76
	v_bfe_u32 v56, v45, 16, 1
	v_add3_u32 v6, v6, v49, s76
	v_add3_u32 v45, v45, v56, s76
	v_lshrrev_b32_e32 v6, 16, v6
	global_store_dwordx4 v[84:85], v[88:91], off offset:64
	v_lshrrev_b32_e32 v45, 16, v45
	s_nop 1
	v_cvt_pk_bf16_f32 v90, v44, v48
	v_cvt_pk_bf16_f32 v89, v7, v35
	v_and_or_b32 v88, v34, s77, v6
	v_and_or_b32 v91, v2, s77, v45
	v_mul_f32_e32 v34, v96, v46
	v_mul_f32_e32 v35, v97, v54
	v_mul_f32_e32 v48, v94, v58
	v_mul_f32_e32 v49, v95, v70
	v_mul_f32_e32 v6, v76, v50
	v_mul_f32_e32 v7, v77, v62
	v_mul_f32_e32 v44, v80, v66
	v_mul_f32_e32 v45, v81, v74
	v_mov_b32_e32 v54, v47
	v_mov_b32_e32 v70, v59
	global_store_dwordx4 v[84:85], v[88:91], off offset:2112
	v_mov_b32_e32 v62, v51
	s_nop 1
	v_cvt_pk_bf16_f32 v90, v44, v48
	v_cvt_pk_bf16_f32 v89, v7, v35
	v_cvt_pk_bf16_f32 v88, v6, v34
	v_pk_mul_f32 v[34:35], v[54:55], v[96:97]
	v_mov_b32_e32 v74, v67
	v_pk_mul_f32 v[46:47], v[70:71], v[94:95]
	v_cvt_pk_bf16_f32 v91, v45, v49
	v_pk_mul_f32 v[6:7], v[62:63], v[76:77]
	v_pk_mul_f32 v[44:45], v[74:75], v[80:81]
	v_bfe_u32 v2, v47, 16, 1
	v_bfe_u32 v50, v34, 16, 1
	v_add3_u32 v34, v34, v50, s76
	v_add3_u32 v2, v47, v2, s76
	v_bfe_u32 v47, v6, 16, 1
	v_bfe_u32 v50, v45, 16, 1
	v_add3_u32 v45, v45, v50, s76
	v_add3_u32 v6, v6, v47, s76
	v_lshrrev_b32_e32 v6, 16, v6
	v_lshrrev_b32_e32 v45, 16, v45
	v_and_or_b32 v47, v2, s77, v45
	v_cvt_pk_bf16_f32 v46, v44, v46
	v_cvt_pk_bf16_f32 v45, v7, v35
	v_and_or_b32 v44, v34, s77, v6
	global_store_dwordx4 v[86:87], v[44:47], off offset:2112
	s_waitcnt vmcnt(9)
	s_waitcnt vmcnt(7)
	s_waitcnt vmcnt(6)
	s_waitcnt vmcnt(4)
	v_mul_f32_e32 v34, v82, v24
	v_mul_f32_e32 v35, v83, v36
	v_mul_f32_e32 v44, v32, v20
	v_mul_f32_e32 v45, v33, v12
	s_waitcnt vmcnt(3)
	v_mul_f32_e32 v6, v4, v28
	v_mul_f32_e32 v7, v5, v40
	v_mul_f32_e32 v46, v78, v16
	v_mul_f32_e32 v47, v79, v8
	v_cvt_pk_bf16_f32 v46, v44, v46
	v_mov_b32_e32 v36, v25
	v_cvt_pk_bf16_f32 v47, v45, v47
	v_cvt_pk_bf16_f32 v45, v7, v35
	v_mov_b32_e32 v40, v29
	v_pk_mul_f32 v[24:25], v[36:37], v[82:83]
	v_mul_f32_e32 v8, v78, v17
	v_mul_f32_e32 v9, v79, v9
	v_cvt_pk_bf16_f32 v44, v6, v34
	v_pk_mul_f32 v[6:7], v[40:41], v[4:5]
	v_mul_f32_e32 v12, v32, v21
	v_mul_f32_e32 v13, v33, v13
	v_bfe_u32 v2, v9, 16, 1
	v_bfe_u32 v20, v24, 16, 1
	v_add3_u32 v20, v24, v20, s76
	v_add3_u32 v2, v9, v2, s76
	v_bfe_u32 v9, v6, 16, 1
	v_bfe_u32 v24, v13, 16, 1
	v_add3_u32 v13, v13, v24, s76
	v_add3_u32 v6, v6, v9, s76
	v_lshrrev_b32_e32 v6, 16, v6
	v_lshrrev_b32_e32 v9, 16, v13
	v_and_or_b32 v9, v2, s77, v9
	v_cvt_pk_bf16_f32 v8, v12, v8
	v_cvt_pk_bf16_f32 v7, v7, v25
	v_and_or_b32 v6, v20, s77, v6
	global_store_dwordx4 v[84:85], v[6:9], off offset:2144
	s_nop 1
	v_mul_f32_e32 v8, v82, v26
	s_nop 1
	v_mul_f32_e32 v9, v83, v38
	v_mul_f32_e32 v16, v78, v18
	v_mul_f32_e32 v17, v79, v10
	v_mul_f32_e32 v6, v4, v30
	v_mul_f32_e32 v7, v5, v42
	v_mul_f32_e32 v12, v32, v22
	v_mul_f32_e32 v13, v33, v14
	v_bfe_u32 v14, v9, 16, 1
	v_bfe_u32 v18, v8, 16, 1
	v_add3_u32 v18, v8, v18, s76
	v_add3_u32 v14, v9, v14, s76
	v_bfe_u32 v9, v6, 16, 1
	v_bfe_u32 v10, v7, 16, 1
	v_add3_u32 v7, v7, v10, s76
	v_add3_u32 v6, v6, v9, s76
	v_lshrrev_b32_e32 v6, 16, v6
	v_lshrrev_b32_e32 v7, 16, v7
	v_mov_b32_e32 v42, v31
	v_cvt_pk_bf16_f32 v9, v13, v17
	v_cvt_pk_bf16_f32 v8, v12, v16
	v_and_or_b32 v7, v14, s77, v7
	v_and_or_b32 v6, v18, s77, v6
	v_pk_mul_f32 v[4:5], v[42:43], v[4:5]
	v_mov_b32_e32 v38, v27
	global_store_dwordx4 v[86:87], v[6:9], off offset:96
	v_and_b32_sdwa v2, v5, v171 dst_sel:DWORD dst_unused:UNUSED_PAD src0_sel:WORD_1 src1_sel:DWORD
	v_add3_u32 v2, v5, v2, s76
	v_pk_mul_f32 v[6:7], v[38:39], v[82:83]
	v_and_b32_sdwa v8, v4, v171 dst_sel:DWORD dst_unused:UNUSED_PAD src0_sel:WORD_1 src1_sel:DWORD
	v_add3_u32 v4, v4, v8, s76
	v_and_b32_sdwa v8, v6, v171 dst_sel:DWORD dst_unused:UNUSED_PAD src0_sel:WORD_1 src1_sel:DWORD
	v_add3_u32 v6, v6, v8, s76
	v_and_b32_sdwa v5, v7, v171 dst_sel:DWORD dst_unused:UNUSED_PAD src0_sel:WORD_1 src1_sel:DWORD
	v_and_b32_e32 v6, 0xffff0000, v6
	v_add3_u32 v5, v7, v5, s76
	v_or_b32_sdwa v4, v6, v4 dst_sel:DWORD dst_unused:UNUSED_PAD src0_sel:DWORD src1_sel:WORD_1
	v_mov_b32_e32 v18, v23
	v_mov_b32_e32 v6, v32
	v_mov_b32_e32 v7, v78
	v_pk_mul_f32 v[6:7], v[18:19], v[6:7]
	v_and_b32_e32 v5, 0xffff0000, v5
	v_and_b32_sdwa v8, v6, v171 dst_sel:DWORD dst_unused:UNUSED_PAD src0_sel:WORD_1 src1_sel:DWORD
	v_mov_b32_e32 v10, v15
	v_mov_b32_e32 v78, v33
	v_or_b32_sdwa v5, v5, v2 dst_sel:DWORD dst_unused:UNUSED_PAD src0_sel:DWORD src1_sel:WORD_1
	v_and_b32_sdwa v2, v7, v171 dst_sel:DWORD dst_unused:UNUSED_PAD src0_sel:WORD_1 src1_sel:DWORD
	v_add3_u32 v6, v6, v8, s76
	v_pk_mul_f32 v[8:9], v[10:11], v[78:79]
	v_add3_u32 v2, v7, v2, s76
	v_lshrrev_b32_e32 v6, 16, v6
	v_and_b32_sdwa v7, v8, v171 dst_sel:DWORD dst_unused:UNUSED_PAD src0_sel:WORD_1 src1_sel:DWORD
	v_and_or_b32 v6, v2, s77, v6
	v_and_b32_sdwa v2, v9, v171 dst_sel:DWORD dst_unused:UNUSED_PAD src0_sel:WORD_1 src1_sel:DWORD
	v_add3_u32 v7, v8, v7, s76
	v_add3_u32 v2, v9, v2, s76
	v_lshrrev_b32_e32 v7, 16, v7
	v_and_or_b32 v7, v2, s77, v7
	s_mov_b64 s[62:63], 0
	global_store_dwordx4 v[86:87], v[88:91], off offset:64
	global_store_dwordx4 v[84:85], v[44:47], off offset:96

.LBB0_578:
	s_mov_b32 s8, 0
	s_and_b64 vcc, exec, s[6:7]
	s_cbranch_vccz .LBB0_580
	s_mov_b64 s[6:7], s[0:1]
	s_load_dwordx2 s[10:11], s[6:7], 0x78
	s_mov_b64 s[6:7], s[0:1]
	s_load_dwordx2 s[48:49], s[6:7], 0xa8
	s_mov_b64 s[6:7], s[0:1]
	s_load_dwordx2 s[6:7], s[6:7], 0x20
	s_waitcnt lgkmcnt(0)
	s_add_u32 s6, s6, 0x1000
	s_addc_u32 s7, s7, 0
	s_add_i32 s8, s77, 32
	s_and_b32 s50, s8, 0xff
	s_mulk_i32 s50, 0xab
	s_lshr_b32 s50, s50, 10
	s_mul_i32 s51, s50, 6
	s_sub_i32 s8, s8, s51
	s_and_b32 s8, s8, 0xff
	v_lshl_or_b32 v4, s8, 7, v83
	v_lshlrev_b32_e32 v84, 11, v4
	v_lshl_add_u64 v[2:3], s[48:49], 0, v[84:85]
	s_lshl_b32 s8, s50, 7
	v_lshl_add_u64 v[2:3], v[2:3], 0, s[8:9]
	v_lshlrev_b32_e32 v84, 1, v82
	v_lshl_or_b32 v72, s50, 6, v82
	v_lshl_add_u64 v[98:99], v[2:3], 0, v[84:85]
	v_lshlrev_b32_e32 v84, 2, v4
	v_mul_u32_u24_e32 v4, 0x300, v72
	v_lshl_add_u64 v[70:71], s[10:11], 0, v[84:85]
	v_lshlrev_b32_e32 v84, 2, v4
	v_mad_u64_u32 v[2:3], s[10:11], v72, s73, v[70:71]
	v_lshl_add_u64 v[68:69], v[70:71], 0, v[84:85]
	global_load_dwordx4 v[46:49], v[2:3], off nt
	global_load_dwordx4 v[42:45], v[68:69], off offset:3072 nt
	v_add_co_u32_e32 v2, vcc, s61, v68
	s_mov_b32 s8, 0xc000
	s_nop 0
	v_addc_co_u32_e32 v3, vcc, 0, v69, vcc
	v_add_co_u32_e32 v4, vcc, s74, v68
	v_or_b32_e32 v10, 16, v72
	s_nop 0
	v_addc_co_u32_e32 v5, vcc, 0, v69, vcc
	global_load_dwordx4 v[54:57], v[2:3], off offset:2048 nt
	global_load_dwordx4 v[50:53], v[4:5], off offset:1024 nt
	v_lshlrev_b32_e32 v2, 2, v72
	global_load_dwordx4 v[58:61], v2, s[6:7] offset:16
	global_load_dwordx4 v[74:77], v2, s[6:7]
	v_add_co_u32_e32 v2, vcc, s62, v68
	s_mov_b64 s[10:11], 0x5000000
	s_nop 0
	v_addc_co_u32_e32 v3, vcc, 0, v69, vcc
	global_load_dwordx4 v[78:81], v[2:3], off nt
	global_load_dwordx4 v[62:65], v[2:3], off offset:3072 nt
	v_add_co_u32_e32 v2, vcc, s63, v68
	v_lshlrev_b32_e32 v6, 2, v10
	s_nop 0
	v_addc_co_u32_e32 v3, vcc, 0, v69, vcc
	global_load_dwordx4 v[86:89], v[2:3], off offset:2048 nt
	v_add_co_u32_e32 v2, vcc, s75, v68
	v_lshl_add_u64 v[66:67], v[98:99], 0, s[10:11]
	s_nop 0
	v_addc_co_u32_e32 v3, vcc, 0, v69, vcc
	global_load_dwordx4 v[90:93], v[2:3], off offset:1024 nt
	v_add_co_u32_e32 v12, vcc, s8, v68
	s_mov_b32 s8, 0xd000
	s_nop 0
	v_addc_co_u32_e32 v13, vcc, 0, v69, vcc
	v_add_co_u32_e32 v14, vcc, s8, v68
	s_mov_b32 s8, 0x10000
	s_nop 0
	v_addc_co_u32_e32 v15, vcc, 0, v69, vcc
	v_add_co_u32_e32 v16, vcc, s78, v68
	v_mad_u64_u32 v[10:11], s[10:11], v10, s73, v[70:71]
	s_nop 0
	v_addc_co_u32_e32 v17, vcc, 0, v69, vcc
	v_add_co_u32_e32 v26, vcc, s80, v68
	global_load_dwordx4 v[2:5], v6, s[6:7] offset:16
	s_nop 0
	global_load_dwordx4 v[6:9], v6, s[6:7]
	v_addc_co_u32_e32 v27, vcc, 0, v69, vcc
	v_add_co_u32_e32 v28, vcc, s8, v68
	s_mov_b32 s8, 0x5001000
	s_nop 0
	v_addc_co_u32_e32 v29, vcc, 0, v69, vcc
	v_add_co_u32_e32 v94, vcc, s79, v68
	s_waitcnt vmcnt(10)
	v_mov_b32_e32 v96, v42
	v_addc_co_u32_e32 v95, vcc, 0, v69, vcc
	global_load_dwordx4 v[18:21], v[10:11], off nt
	global_load_dwordx4 v[30:33], v[12:13], off offset:3072 nt
	global_load_dwordx4 v[38:41], v[14:15], off offset:2048 nt
	global_load_dwordx4 v[34:37], v[16:17], off offset:1024 nt
	global_load_dwordx4 v[22:25], v[26:27], off nt
	s_nop 0
	global_load_dwordx4 v[10:13], v[26:27], off offset:3072 nt
	s_nop 0
	global_load_dwordx4 v[26:29], v[28:29], off offset:2048 nt
	s_nop 0
	global_load_dwordx4 v[14:17], v[94:95], off offset:1024 nt
	s_waitcnt vmcnt(17)
	s_waitcnt vmcnt(16)
	v_mov_b32_e32 v97, v50
	s_waitcnt vmcnt(15)
	v_mov_b32_e32 v111, v60
	s_waitcnt vmcnt(14)
	v_mov_b32_e32 v108, v74
	v_mov_b32_e32 v109, v76
	v_mov_b32_e32 v76, v75
	v_mov_b32_e32 v60, v59
	v_mul_f32_e32 v94, v108, v46
	v_mul_f32_e32 v95, v109, v54
	v_pk_mul_f32 v[74:75], v[96:97], v[76:77]
	s_waitcnt vmcnt(12)
	v_mov_b32_e32 v112, v62
	v_mov_b32_e32 v110, v58
	s_waitcnt vmcnt(11)
	v_mul_f32_e32 v96, v110, v78
	v_mul_f32_e32 v97, v111, v86
	s_waitcnt vmcnt(10)
	v_mov_b32_e32 v113, v90
	v_pk_mul_f32 v[58:59], v[112:113], v[60:61]
	v_cvt_pk_bf16_f32 v95, v95, v75
	v_cvt_pk_bf16_f32 v94, v94, v74
	v_mov_b32_e32 v54, v47
	v_mov_b32_e32 v50, v43
	v_mov_b32_e32 v90, v63
	v_cvt_pk_bf16_f32 v97, v97, v59
	v_cvt_pk_bf16_f32 v96, v96, v58
	v_pk_mul_f32 v[46:47], v[54:55], v[108:109]
	v_pk_mul_f32 v[42:43], v[50:51], v[76:77]
	v_mov_b32_e32 v86, v79
	v_pk_mul_f32 v[54:55], v[90:91], v[60:61]
	v_pk_mul_f32 v[50:51], v[86:87], v[110:111]
	v_add_co_u32_e32 v58, vcc, s8, v98
	v_addc_co_u32_e32 v59, vcc, 0, v99, vcc
	global_store_dwordx4 v[58:59], v[94:97], off offset:-4096
	s_mov_b32 s8, 0x19000
	s_nop 0
	v_cvt_pk_bf16_f32 v97, v51, v55
	v_cvt_pk_bf16_f32 v96, v50, v54
	v_cvt_pk_bf16_f32 v95, v47, v43
	v_cvt_pk_bf16_f32 v94, v46, v42
	v_mul_f32_e32 v46, v76, v44
	v_mul_f32_e32 v47, v77, v52
	v_mul_f32_e32 v54, v60, v64
	v_mul_f32_e32 v55, v61, v92
	v_mov_b32_e32 v42, v48
	v_mul_f32_e32 v50, v110, v80
	v_mul_f32_e32 v51, v111, v88
	v_bfe_u32 v48, v54, 16, 1
	v_bfe_u32 v52, v47, 16, 1
	v_mul_f32_e32 v42, v108, v42
	v_mul_f32_e32 v43, v109, v56
	v_bfe_u32 v44, v55, 16, 1
	v_bfe_u32 v56, v46, 16, 1
	v_add3_u32 v48, v54, v48, s68
	v_add3_u32 v47, v47, v52, s68
	v_bfe_u32 v52, v50, 16, 1
	v_bfe_u32 v54, v51, 16, 1
	v_add3_u32 v44, v55, v44, s68
	v_add3_u32 v46, v46, v56, s68
	v_bfe_u32 v55, v42, 16, 1
	v_bfe_u32 v56, v43, 16, 1
	v_add3_u32 v51, v51, v54, s68
	v_add3_u32 v50, v50, v52, s68
	v_add3_u32 v43, v43, v56, s68
	v_add3_u32 v42, v42, v55, s68
	v_lshrrev_b32_e32 v50, 16, v50
	v_lshrrev_b32_e32 v51, 16, v51
	v_mov_b32_e32 v52, v45
	v_mov_b32_e32 v92, v65
	global_store_dwordx4 v[66:67], v[94:97], off offset:2048
	v_lshrrev_b32_e32 v42, 16, v42
	v_lshrrev_b32_e32 v43, 16, v43
	v_and_or_b32 v97, v44, s69, v51
	v_and_or_b32 v96, v48, s69, v50
	v_mov_b32_e32 v56, v49
	v_pk_mul_f32 v[44:45], v[52:53], v[76:77]
	v_mov_b32_e32 v88, v81
	v_pk_mul_f32 v[48:49], v[92:93], v[60:61]
	v_and_or_b32 v95, v47, s69, v43
	v_and_or_b32 v94, v46, s69, v42
	v_pk_mul_f32 v[42:43], v[56:57], v[108:109]
	v_pk_mul_f32 v[46:47], v[88:89], v[110:111]
	v_bfe_u32 v50, v49, 16, 1
	v_bfe_u32 v51, v48, 16, 1
	v_bfe_u32 v52, v45, 16, 1
	v_bfe_u32 v53, v44, 16, 1
	v_add3_u32 v48, v48, v51, s68
	v_add3_u32 v49, v49, v50, s68
	v_add3_u32 v50, v44, v53, s68
	v_add3_u32 v51, v45, v52, s68
	v_bfe_u32 v44, v46, 16, 1
	v_bfe_u32 v45, v47, 16, 1
	v_bfe_u32 v52, v42, 16, 1
	v_bfe_u32 v53, v43, 16, 1
	v_add3_u32 v45, v47, v45, s68
	v_add3_u32 v44, v46, v44, s68
	v_add3_u32 v43, v43, v53, s68
	v_add3_u32 v42, v42, v52, s68
	v_lshrrev_b32_e32 v44, 16, v44
	v_lshrrev_b32_e32 v45, 16, v45
	v_lshrrev_b32_e32 v42, 16, v42
	v_lshrrev_b32_e32 v43, 16, v43
	v_and_or_b32 v45, v49, s69, v45
	v_and_or_b32 v44, v48, s69, v44
	v_and_or_b32 v43, v51, s69, v43
	v_and_or_b32 v42, v50, s69, v42
	global_store_dwordx4 v[58:59], v[42:45], off offset:2048
	s_waitcnt vmcnt(11)
	v_mov_b32_e32 v47, v8
	v_mov_b32_e32 v8, v7
	s_waitcnt vmcnt(9)
	v_mov_b32_e32 v44, v30
	s_waitcnt vmcnt(7)
	v_mov_b32_e32 v45, v34
	v_mov_b32_e32 v49, v4
	s_waitcnt vmcnt(5)
	v_mov_b32_e32 v50, v10
	s_waitcnt vmcnt(3)
	v_mov_b32_e32 v51, v14
	v_mov_b32_e32 v4, v3
	v_mov_b32_e32 v46, v6
	v_pk_mul_f32 v[6:7], v[44:45], v[8:9]
	v_mov_b32_e32 v48, v2
	v_pk_mul_f32 v[2:3], v[50:51], v[4:5]
	v_mul_f32_e32 v42, v46, v18
	v_mul_f32_e32 v43, v47, v38
	v_mul_f32_e32 v44, v48, v22
	v_mul_f32_e32 v45, v49, v26
	v_bfe_u32 v14, v2, 16, 1
	v_bfe_u32 v18, v7, 16, 1
	v_bfe_u32 v10, v3, 16, 1
	v_add3_u32 v7, v7, v18, s68
	v_add3_u32 v2, v2, v14, s68
	v_bfe_u32 v14, v45, 16, 1
	v_bfe_u32 v22, v43, 16, 1
	v_add3_u32 v3, v3, v10, s68
	v_bfe_u32 v10, v44, 16, 1
	v_add3_u32 v14, v45, v14, s68
	v_add3_u32 v22, v43, v22, s68
	v_add3_u32 v10, v44, v10, s68
	v_lshrrev_b32_e32 v14, 16, v14
	v_lshrrev_b32_e32 v22, 16, v22
	v_mov_b32_e32 v34, v31
	v_lshrrev_b32_e32 v10, 16, v10
	v_and_or_b32 v45, v3, s69, v14
	v_and_or_b32 v43, v7, s69, v22
	v_cvt_pk_bf16_f32 v42, v42, v6
	v_mov_b32_e32 v38, v19
	v_pk_mul_f32 v[6:7], v[34:35], v[8:9]
	v_mov_b32_e32 v14, v11
	v_and_or_b32 v44, v2, s69, v10
	v_pk_mul_f32 v[2:3], v[38:39], v[46:47]
	v_mov_b32_e32 v26, v23
	v_pk_mul_f32 v[10:11], v[14:15], v[4:5]
	v_pk_mul_f32 v[18:19], v[26:27], v[48:49]
	v_bfe_u32 v14, v11, 16, 1
	v_add3_u32 v11, v11, v14, s68
	v_bfe_u32 v15, v19, 16, 1
	v_add3_u32 v15, v19, v15, s68
	global_store_dwordx4 v[66:67], v[42:45], off offset:32
	v_lshrrev_b32_e32 v15, 16, v15
	s_nop 1
	v_cvt_pk_bf16_f32 v43, v3, v7
	v_cvt_pk_bf16_f32 v42, v2, v6
	v_and_or_b32 v45, v11, s69, v15
	v_cvt_pk_bf16_f32 v44, v18, v10
	v_mul_f32_e32 v6, v8, v32
	v_mul_f32_e32 v7, v9, v36
	v_mul_f32_e32 v2, v46, v20
	v_mul_f32_e32 v3, v47, v40
	v_mul_f32_e32 v14, v4, v12
	v_mul_f32_e32 v15, v5, v16
	v_mul_f32_e32 v10, v48, v24
	v_mul_f32_e32 v11, v49, v28
	v_mov_b32_e32 v36, v33
	v_mov_b32_e32 v16, v13
	global_store_dwordx4 v[66:67], v[42:45], off offset:2080
	s_nop 1
	v_cvt_pk_bf16_f32 v43, v3, v7
	s_nop 1
	v_cvt_pk_bf16_f32 v42, v2, v6
	v_mov_b32_e32 v40, v21
	v_pk_mul_f32 v[6:7], v[36:37], v[8:9]
	v_mov_b32_e32 v28, v25
	v_pk_mul_f32 v[4:5], v[16:17], v[4:5]
	v_cvt_pk_bf16_f32 v45, v11, v15
	v_cvt_pk_bf16_f32 v44, v10, v14
	v_pk_mul_f32 v[2:3], v[40:41], v[46:47]
	v_pk_mul_f32 v[8:9], v[28:29], v[48:49]
	v_cvt_pk_bf16_f32 v5, v9, v5
	v_cvt_pk_bf16_f32 v4, v8, v4
	v_cvt_pk_bf16_f32 v3, v3, v7
	v_cvt_pk_bf16_f32 v2, v2, v6
	global_store_dwordx4 v[58:59], v[2:5], off offset:2080
	v_or_b32_e32 v6, 32, v72
	global_store_dwordx4 v[58:59], v[94:97], off
	v_add_co_u32_e32 v4, vcc, s66, v68
	global_store_dwordx4 v[58:59], v[42:45], off offset:32
	v_mad_u64_u32 v[2:3], s[10:11], v6, s73, v[70:71]
	v_addc_co_u32_e32 v5, vcc, 0, v69, vcc
	global_load_dwordx4 v[42:45], v[2:3], off nt
	global_load_dwordx4 v[46:49], v[4:5], off offset:3072 nt
	v_add_co_u32_e32 v2, vcc, s8, v68
	s_mov_b32 s8, 0x1a000
	s_nop 0
	v_addc_co_u32_e32 v3, vcc, 0, v69, vcc
	v_add_co_u32_e32 v4, vcc, s8, v68
	s_mov_b32 s8, 0x1b000
	s_nop 0
	v_addc_co_u32_e32 v5, vcc, 0, v69, vcc
	global_load_dwordx4 v[50:53], v[2:3], off offset:2048 nt
	global_load_dwordx4 v[54:57], v[4:5], off offset:1024 nt
	v_lshlrev_b32_e32 v2, 2, v6
	global_load_dwordx4 v[60:63], v2, s[6:7] offset:16
	global_load_dwordx4 v[74:77], v2, s[6:7]
	v_add_co_u32_e32 v2, vcc, s8, v68
	s_mov_b32 s8, 0x1c000
	s_nop 0
	v_addc_co_u32_e32 v3, vcc, 0, v69, vcc
	global_load_dwordx4 v[78:81], v[2:3], off nt
	global_load_dwordx4 v[86:89], v[2:3], off offset:3072 nt
	v_add_co_u32_e32 v2, vcc, s8, v68
	v_or_b32_e32 v34, 48, v72
	s_nop 0
	v_addc_co_u32_e32 v3, vcc, 0, v69, vcc
	global_load_dwordx4 v[90:93], v[2:3], off offset:2048 nt
	v_add_co_u32_e32 v2, vcc, s82, v68
	v_lshlrev_b32_e32 v38, 2, v34
	s_nop 0
	v_addc_co_u32_e32 v3, vcc, 0, v69, vcc
	global_load_dwordx4 v[94:97], v[2:3], off offset:1024 nt
	v_add_co_u32_e32 v4, vcc, s83, v68
	v_mad_u64_u32 v[2:3], s[10:11], v34, s73, v[70:71]
	s_nop 0
	v_addc_co_u32_e32 v5, vcc, 0, v69, vcc
	v_add_co_u32_e32 v10, vcc, s84, v68
	global_load_dwordx4 v[6:9], v[2:3], off nt
	s_nop 0
	global_load_dwordx4 v[2:5], v[4:5], off offset:3072 nt
	v_addc_co_u32_e32 v11, vcc, 0, v69, vcc
	v_add_co_u32_e32 v12, vcc, s85, v68
	s_mov_b32 s8, 4
	s_nop 0
	v_addc_co_u32_e32 v13, vcc, 0, v69, vcc
	v_add_co_u32_e32 v14, vcc, s86, v68
	global_load_dwordx4 v[18:21], v[10:11], off offset:2048 nt
	s_nop 0
	global_load_dwordx4 v[10:13], v[12:13], off offset:1024 nt
	v_addc_co_u32_e32 v15, vcc, 0, v69, vcc
	v_add_co_u32_e32 v26, vcc, s87, v68
	global_load_dwordx4 v[22:25], v[14:15], off nt
	s_nop 0
	global_load_dwordx4 v[14:17], v[14:15], off offset:3072 nt
	v_addc_co_u32_e32 v27, vcc, 0, v69, vcc
	v_add_co_u32_e32 v28, vcc, s88, v68
	s_waitcnt vmcnt(15)
	v_addc_co_u32_e32 v29, vcc, 0, v69, vcc
	global_load_dwordx4 v[30:33], v[26:27], off offset:2048 nt
	s_nop 0
	global_load_dwordx4 v[26:29], v[28:29], off offset:1024 nt
	s_nop 0
	global_load_dwordx4 v[34:37], v38, s[6:7] offset:16
	s_nop 0
	global_load_dwordx4 v[38:41], v38, s[6:7]
	s_waitcnt vmcnt(18)
	s_waitcnt vmcnt(17)
	s_waitcnt vmcnt(16)
	s_waitcnt vmcnt(14)
	v_mov_b32_e32 v73, v76
	v_mov_b32_e32 v76, v75
	v_mov_b32_e32 v72, v74
	v_mul_f32_e32 v68, v76, v46
	v_mul_f32_e32 v69, v77, v54
	v_mov_b32_e32 v75, v62
	v_mov_b32_e32 v62, v61
	s_waitcnt vmcnt(12)
	v_mov_b32_e32 v98, v86
	v_mul_f32_e32 v64, v72, v42
	v_mul_f32_e32 v65, v73, v50
	v_mov_b32_e32 v74, v60
	s_waitcnt vmcnt(11)
	v_mul_f32_e32 v70, v74, v78
	v_mul_f32_e32 v71, v75, v90
	s_waitcnt vmcnt(10)
	v_mov_b32_e32 v99, v94
	v_pk_mul_f32 v[60:61], v[98:99], v[62:63]
	v_cvt_pk_bf16_f32 v68, v64, v68
	v_mov_b32_e32 v54, v47
	v_mov_b32_e32 v94, v87
	v_cvt_pk_bf16_f32 v70, v70, v60
	v_cvt_pk_bf16_f32 v69, v65, v69
	v_mov_b32_e32 v50, v43
	v_pk_mul_f32 v[46:47], v[54:55], v[76:77]
	v_mov_b32_e32 v90, v79
	v_pk_mul_f32 v[54:55], v[94:95], v[62:63]
	v_cvt_pk_bf16_f32 v71, v71, v61
	v_pk_mul_f32 v[42:43], v[50:51], v[72:73]
	v_pk_mul_f32 v[50:51], v[90:91], v[74:75]
	global_store_dwordx4 v[66:67], v[68:71], off offset:64
	s_nop 1
	v_cvt_pk_bf16_f32 v71, v51, v55
	v_cvt_pk_bf16_f32 v70, v50, v54
	v_cvt_pk_bf16_f32 v69, v43, v47
	v_cvt_pk_bf16_f32 v68, v42, v46
	v_mul_f32_e32 v46, v76, v48
	v_mul_f32_e32 v47, v77, v56
	v_mul_f32_e32 v54, v62, v88
	v_mul_f32_e32 v55, v63, v96
	v_mov_b32_e32 v43, v52
	v_mul_f32_e32 v50, v74, v80
	v_mul_f32_e32 v51, v75, v92
	v_bfe_u32 v52, v47, 16, 1
	v_mul_f32_e32 v42, v72, v44
	v_mul_f32_e32 v43, v73, v43
	v_add3_u32 v47, v47, v52, s68
	v_bfe_u32 v56, v43, 16, 1
	v_add3_u32 v43, v43, v56, s68
	v_mov_b32_e32 v56, v49
	v_mov_b32_e32 v96, v89
	global_store_dwordx4 v[66:67], v[68:71], off offset:2112
	v_lshrrev_b32_e32 v43, 16, v43
	s_nop 1
	v_cvt_pk_bf16_f32 v71, v51, v55
	v_cvt_pk_bf16_f32 v70, v50, v54
	v_mov_b32_e32 v52, v45
	v_pk_mul_f32 v[44:45], v[56:57], v[76:77]
	v_mov_b32_e32 v92, v81
	v_pk_mul_f32 v[48:49], v[96:97], v[62:63]
	v_and_or_b32 v69, v47, s69, v43
	v_cvt_pk_bf16_f32 v68, v42, v46
	v_pk_mul_f32 v[42:43], v[52:53], v[72:73]
	v_pk_mul_f32 v[46:47], v[92:93], v[74:75]
	v_bfe_u32 v52, v45, 16, 1
	v_bfe_u32 v53, v44, 16, 1
	v_add3_u32 v53, v44, v53, s68
	v_add3_u32 v52, v45, v52, s68
	v_bfe_u32 v50, v42, 16, 1
	v_bfe_u32 v51, v43, 16, 1
	v_add3_u32 v43, v43, v51, s68
	v_add3_u32 v42, v42, v50, s68
	v_lshrrev_b32_e32 v42, 16, v42
	v_lshrrev_b32_e32 v43, 16, v43
	v_cvt_pk_bf16_f32 v45, v47, v49
	v_cvt_pk_bf16_f32 v44, v46, v48
	v_and_or_b32 v43, v52, s69, v43
	v_and_or_b32 v42, v53, s69, v42
	global_store_dwordx4 v[58:59], v[42:45], off offset:2112
	s_waitcnt vmcnt(3)
	v_mov_b32_e32 v46, v38
	v_mov_b32_e32 v47, v40
	v_mov_b32_e32 v44, v2
	v_mov_b32_e32 v45, v10
	v_mov_b32_e32 v40, v39
	v_mul_f32_e32 v42, v46, v6
	v_mul_f32_e32 v43, v47, v18
	v_pk_mul_f32 v[38:39], v[44:45], v[40:41]
	v_mov_b32_e32 v48, v34
	v_mov_b32_e32 v49, v36
	v_mul_f32_e32 v44, v48, v22
	v_mul_f32_e32 v45, v49, v30
	v_mov_b32_e32 v50, v14
	v_mov_b32_e32 v51, v26
	v_mov_b32_e32 v36, v35
	v_pk_mul_f32 v[34:35], v[50:51], v[36:37]
	v_cvt_pk_bf16_f32 v43, v43, v39
	v_cvt_pk_bf16_f32 v42, v42, v38
	v_mov_b32_e32 v10, v3
	v_mov_b32_e32 v26, v15
	v_cvt_pk_bf16_f32 v45, v45, v35
	v_cvt_pk_bf16_f32 v44, v44, v34
	v_mov_b32_e32 v18, v7
	v_pk_mul_f32 v[2:3], v[10:11], v[40:41]
	v_mov_b32_e32 v30, v23
	v_pk_mul_f32 v[14:15], v[26:27], v[36:37]
	v_pk_mul_f32 v[6:7], v[18:19], v[46:47]
	v_pk_mul_f32 v[10:11], v[30:31], v[48:49]
	global_store_dwordx4 v[66:67], v[42:45], off offset:96
	global_store_dwordx4 v[58:59], v[68:71], off offset:64
	s_nop 0
	v_cvt_pk_bf16_f32 v45, v11, v15
	v_cvt_pk_bf16_f32 v44, v10, v14
	v_cvt_pk_bf16_f32 v43, v7, v3
	v_cvt_pk_bf16_f32 v42, v6, v2
	v_mul_f32_e32 v6, v40, v4
	v_mul_f32_e32 v7, v41, v12
	v_mul_f32_e32 v14, v36, v16
	v_mul_f32_e32 v15, v37, v28
	v_mov_b32_e32 v2, v8
	v_mul_f32_e32 v10, v48, v24
	v_mul_f32_e32 v11, v49, v32
	v_bfe_u32 v8, v14, 16, 1
	v_mul_f32_e32 v2, v46, v2
	v_mul_f32_e32 v3, v47, v20
	v_add3_u32 v8, v14, v8, s68
	v_bfe_u32 v12, v10, 16, 1
	v_add3_u32 v10, v10, v12, s68
	v_lshrrev_b32_e32 v10, 16, v10
	v_mov_b32_e32 v12, v5
	v_mov_b32_e32 v28, v17
	global_store_dwordx4 v[66:67], v[42:45], off offset:2144
	s_nop 1
	v_cvt_pk_bf16_f32 v45, v11, v15
	s_nop 1
	v_and_or_b32 v44, v8, s69, v10
	v_mov_b32_e32 v20, v9
	v_pk_mul_f32 v[4:5], v[12:13], v[40:41]
	v_mov_b32_e32 v32, v25
	v_pk_mul_f32 v[8:9], v[28:29], v[36:37]
	v_cvt_pk_bf16_f32 v43, v3, v7
	v_cvt_pk_bf16_f32 v42, v2, v6
	v_pk_mul_f32 v[2:3], v[20:21], v[46:47]
	v_pk_mul_f32 v[6:7], v[32:33], v[48:49]
	v_bfe_u32 v12, v5, 16, 1
	v_bfe_u32 v13, v4, 16, 1
	v_add3_u32 v13, v4, v13, s68
	v_add3_u32 v12, v5, v12, s68
	v_bfe_u32 v10, v2, 16, 1
	v_bfe_u32 v11, v3, 16, 1
	v_add3_u32 v3, v3, v11, s68
	v_add3_u32 v2, v2, v10, s68
	v_lshrrev_b32_e32 v2, 16, v2
	v_lshrrev_b32_e32 v3, 16, v3
	v_cvt_pk_bf16_f32 v5, v7, v9
	v_cvt_pk_bf16_f32 v4, v6, v8
	v_and_or_b32 v3, v12, s69, v3
	v_and_or_b32 v2, v13, s69, v2
	global_store_dwordx4 v[58:59], v[42:45], off offset:96
	global_store_dwordx4 v[58:59], v[2:5], off offset:2144

.LBB0_590:
	s_waitcnt vmcnt(15)
	s_waitcnt vmcnt(13)
	v_mul_f32_e32 v44, v74, v46
	v_mul_f32_e32 v45, v75, v54
	s_waitcnt vmcnt(12)
	s_waitcnt vmcnt(11)
	s_waitcnt vmcnt(9)
	v_mul_f32_e32 v80, v94, v38
	v_mul_f32_e32 v81, v95, v50
	v_mul_f32_e32 v88, v78, v62
	v_mul_f32_e32 v89, v79, v70
	s_waitcnt vmcnt(8)
	v_bfe_u32 v62, v45, 16, 1
	v_mul_f32_e32 v90, v92, v58
	v_mul_f32_e32 v91, v93, v66
	v_bfe_u32 v50, v81, 16, 1
	v_bfe_u32 v58, v44, 16, 1
	v_bfe_u32 v66, v88, 16, 1
	v_bfe_u32 v70, v89, 16, 1
	v_add3_u32 v45, v45, v62, s68
	v_bfe_u32 v38, v91, 16, 1
	v_bfe_u32 v54, v80, 16, 1
	v_add3_u32 v50, v81, v50, s68
	v_add3_u32 v70, v89, v70, s68
	v_add3_u32 v66, v88, v66, s68
	v_add3_u32 v44, v44, v58, s68
	v_lshrrev_b32_e32 v45, 16, v45
	v_bfe_u32 v46, v90, 16, 1
	v_add3_u32 v54, v80, v54, s68
	v_add3_u32 v38, v91, v38, s68
	v_lshrrev_b32_e32 v44, 16, v44
	v_lshrrev_b32_e32 v58, 16, v66
	v_lshrrev_b32_e32 v62, 16, v70
	v_and_or_b32 v89, v50, s69, v45
	v_mov_b32_e32 v50, v39
	v_mov_b32_e32 v66, v59
	v_add3_u32 v46, v90, v46, s68
	v_and_or_b32 v91, v38, s69, v62
	v_and_or_b32 v88, v54, s69, v44
	v_mov_b32_e32 v54, v47
	v_pk_mul_f32 v[38:39], v[50:51], v[94:95]
	v_mov_b32_e32 v70, v63
	v_pk_mul_f32 v[50:51], v[66:67], v[92:93]
	v_and_or_b32 v90, v46, s69, v58
	v_pk_mul_f32 v[44:45], v[54:55], v[74:75]
	v_pk_mul_f32 v[46:47], v[70:71], v[78:79]
	v_cvt_pk_bf16_f32 v47, v47, v51
	v_cvt_pk_bf16_f32 v46, v46, v50
	v_cvt_pk_bf16_f32 v45, v45, v39
	v_cvt_pk_bf16_f32 v44, v44, v38
	global_store_dwordx4 v[86:87], v[44:47], off offset:576
	s_nop 1
	v_mul_f32_e32 v44, v94, v40
	s_nop 1
	v_mul_f32_e32 v45, v95, v52
	v_mul_f32_e32 v50, v92, v60
	v_mul_f32_e32 v51, v93, v68
	v_mul_f32_e32 v38, v74, v48
	v_mul_f32_e32 v39, v75, v56
	v_mul_f32_e32 v46, v78, v64
	v_mul_f32_e32 v47, v79, v72
	v_cvt_pk_bf16_f32 v47, v47, v51
	v_cvt_pk_bf16_f32 v46, v46, v50
	v_cvt_pk_bf16_f32 v45, v39, v45
	v_cvt_pk_bf16_f32 v44, v38, v44
	v_mov_b32_e32 v52, v41
	v_mov_b32_e32 v68, v61
	global_store_dwordx4 v[86:87], v[44:47], off offset:1088
	v_mov_b32_e32 v56, v49
	v_pk_mul_f32 v[40:41], v[52:53], v[94:95]
	v_mov_b32_e32 v72, v65
	v_pk_mul_f32 v[46:47], v[68:69], v[92:93]
	v_pk_mul_f32 v[38:39], v[56:57], v[74:75]
	v_pk_mul_f32 v[44:45], v[72:73], v[78:79]
	v_bfe_u32 v48, v47, 16, 1
	v_bfe_u32 v49, v46, 16, 1
	v_bfe_u32 v50, v41, 16, 1
	v_bfe_u32 v51, v40, 16, 1
	v_add3_u32 v51, v40, v51, s68
	v_add3_u32 v50, v41, v50, s68
	v_add3_u32 v40, v46, v49, s68
	v_add3_u32 v41, v47, v48, s68
	v_bfe_u32 v46, v38, 16, 1
	v_bfe_u32 v47, v39, 16, 1
	v_bfe_u32 v48, v44, 16, 1
	v_bfe_u32 v49, v45, 16, 1
	v_add3_u32 v45, v45, v49, s68
	v_add3_u32 v44, v44, v48, s68
	v_add3_u32 v39, v39, v47, s68
	v_add3_u32 v38, v38, v46, s68
	v_lshrrev_b32_e32 v38, 16, v38
	v_lshrrev_b32_e32 v39, 16, v39
	v_lshrrev_b32_e32 v44, 16, v44
	v_lshrrev_b32_e32 v45, 16, v45
	v_and_or_b32 v41, v41, s69, v45
	v_and_or_b32 v40, v40, s69, v44
	v_and_or_b32 v39, v50, s69, v39
	v_and_or_b32 v38, v51, s69, v38
	global_store_dwordx4 v[86:87], v[38:41], off offset:1600
	s_waitcnt vmcnt(6)
	s_waitcnt vmcnt(4)
	v_mul_f32_e32 v38, v2, v10
	v_mul_f32_e32 v39, v3, v18
	v_mul_f32_e32 v44, v42, v26
	v_mul_f32_e32 v45, v43, v34
	s_waitcnt vmcnt(3)
	v_mul_f32_e32 v40, v76, v6
	v_mul_f32_e32 v41, v77, v14
	v_mul_f32_e32 v46, v4, v22
	v_mul_f32_e32 v47, v5, v30
	v_bfe_u32 v22, v38, 16, 1
	v_bfe_u32 v18, v40, 16, 1
	v_add3_u32 v22, v38, v22, s68
	v_add3_u32 v18, v40, v18, s68
	v_lshrrev_b32_e32 v22, 16, v22
	v_cvt_pk_bf16_f32 v40, v44, v46
	v_cvt_pk_bf16_f32 v39, v39, v41
	v_and_or_b32 v38, v18, s69, v22
	v_mov_b32_e32 v18, v11
	v_mov_b32_e32 v14, v7
	v_mov_b32_e32 v30, v23
	v_cvt_pk_bf16_f32 v41, v45, v47
	v_pk_mul_f32 v[10:11], v[18:19], v[2:3]
	v_pk_mul_f32 v[6:7], v[14:15], v[76:77]
	v_mov_b32_e32 v34, v27
	v_pk_mul_f32 v[18:19], v[30:31], v[4:5]
	v_pk_mul_f32 v[14:15], v[34:35], v[42:43]
	global_store_dwordx4 v[86:87], v[38:41], off offset:96
	s_mov_b32 s8, 4
	global_store_dwordx4 v[86:87], v[88:91], off offset:64
	v_cvt_pk_bf16_f32 v41, v15, v19
	v_cvt_pk_bf16_f32 v40, v14, v18
	v_cvt_pk_bf16_f32 v39, v11, v7
	v_cvt_pk_bf16_f32 v38, v10, v6
	v_mul_f32_e32 v10, v76, v8
	v_mul_f32_e32 v11, v77, v16
	v_mul_f32_e32 v18, v4, v24
	v_mul_f32_e32 v19, v5, v32
	v_mul_f32_e32 v6, v2, v12
	v_mul_f32_e32 v7, v3, v20
	v_bfe_u32 v12, v18, 16, 1
	v_bfe_u32 v16, v11, 16, 1
	v_mul_f32_e32 v14, v42, v28
	v_mul_f32_e32 v15, v43, v36
	v_bfe_u32 v8, v19, 16, 1
	v_bfe_u32 v20, v10, 16, 1
	v_add3_u32 v11, v11, v16, s68
	v_add3_u32 v12, v18, v12, s68
	v_bfe_u32 v16, v6, 16, 1
	v_bfe_u32 v18, v7, 16, 1
	v_add3_u32 v10, v10, v20, s68
	v_add3_u32 v8, v19, v8, s68
	v_bfe_u32 v19, v14, 16, 1
	v_bfe_u32 v20, v15, 16, 1
	v_add3_u32 v7, v7, v18, s68
	v_add3_u32 v6, v6, v16, s68
	v_add3_u32 v15, v15, v20, s68
	v_add3_u32 v14, v14, v19, s68
	v_lshrrev_b32_e32 v6, 16, v6
	v_lshrrev_b32_e32 v7, 16, v7
	v_mov_b32_e32 v16, v9
	v_mov_b32_e32 v32, v25
	global_store_dwordx4 v[86:87], v[38:41], off offset:608
	v_lshrrev_b32_e32 v14, 16, v14
	v_lshrrev_b32_e32 v15, 16, v15
	v_and_or_b32 v39, v11, s69, v7
	v_and_or_b32 v38, v10, s69, v6
	v_mov_b32_e32 v20, v13
	v_pk_mul_f32 v[6:7], v[16:17], v[76:77]
	v_mov_b32_e32 v36, v29
	v_pk_mul_f32 v[4:5], v[32:33], v[4:5]
	v_and_or_b32 v41, v8, s69, v15
	v_and_or_b32 v40, v12, s69, v14
	v_pk_mul_f32 v[2:3], v[20:21], v[2:3]
	v_pk_mul_f32 v[8:9], v[36:37], v[42:43]
	v_cvt_pk_bf16_f32 v5, v9, v5
	v_cvt_pk_bf16_f32 v4, v8, v4
	v_cvt_pk_bf16_f32 v3, v3, v7
	v_cvt_pk_bf16_f32 v2, v2, v6
	global_store_dwordx4 v[86:87], v[38:41], off offset:1120
	global_store_dwordx4 v[86:87], v[2:5], off offset:1632

.LBB0_598:
	s_waitcnt vmcnt(11)
	s_waitcnt vmcnt(9)
	v_mul_f32_e32 v96, v78, v62
	v_mul_f32_e32 v97, v79, v70
	s_waitcnt vmcnt(8)
	v_mul_f32_e32 v40, v74, v54
	v_mul_f32_e32 v41, v75, v58
	v_mul_f32_e32 v98, v92, v50
	v_mul_f32_e32 v99, v93, v66
	v_mul_f32_e32 v88, v94, v42
	v_mul_f32_e32 v89, v95, v46
	v_bfe_u32 v58, v40, 16, 1
	v_add3_u32 v40, v40, v58, s68
	v_bfe_u32 v54, v88, 16, 1
	v_cvt_pk_bf16_f32 v98, v96, v98
	v_mov_b32_e32 v46, v43
	v_mov_b32_e32 v66, v51
	v_add3_u32 v54, v88, v54, s68
	v_lshrrev_b32_e32 v40, 16, v40
	v_cvt_pk_bf16_f32 v99, v97, v99
	v_cvt_pk_bf16_f32 v97, v41, v89
	v_mov_b32_e32 v58, v55
	v_pk_mul_f32 v[42:43], v[46:47], v[94:95]
	v_mov_b32_e32 v70, v63
	v_pk_mul_f32 v[50:51], v[66:67], v[92:93]
	v_and_or_b32 v96, v54, s69, v40
	v_pk_mul_f32 v[40:41], v[58:59], v[74:75]
	v_pk_mul_f32 v[46:47], v[70:71], v[78:79]
	v_bfe_u32 v54, v51, 16, 1
	v_bfe_u32 v55, v50, 16, 1
	v_bfe_u32 v58, v43, 16, 1
	v_bfe_u32 v59, v42, 16, 1
	v_add3_u32 v59, v42, v59, s68
	v_add3_u32 v58, v43, v58, s68
	v_add3_u32 v42, v50, v55, s68
	v_add3_u32 v43, v51, v54, s68
	v_bfe_u32 v50, v40, 16, 1
	v_bfe_u32 v51, v41, 16, 1
	v_bfe_u32 v54, v46, 16, 1
	v_bfe_u32 v55, v47, 16, 1
	v_add3_u32 v47, v47, v55, s68
	v_add3_u32 v46, v46, v54, s68
	v_add3_u32 v41, v41, v51, s68
	v_add3_u32 v40, v40, v50, s68
	v_lshrrev_b32_e32 v40, 16, v40
	v_lshrrev_b32_e32 v41, 16, v41
	v_lshrrev_b32_e32 v46, 16, v46
	v_lshrrev_b32_e32 v47, 16, v47
	v_and_or_b32 v43, v43, s69, v47
	v_and_or_b32 v42, v42, s69, v46
	v_and_or_b32 v41, v58, s69, v41
	v_and_or_b32 v40, v59, s69, v40
	global_store_dwordx4 v[86:87], v[40:43], off offset:2048
	s_nop 1
	v_mul_f32_e32 v42, v94, v44
	s_nop 1
	v_mul_f32_e32 v43, v95, v48
	v_mul_f32_e32 v50, v92, v52
	v_mul_f32_e32 v51, v93, v68
	v_mul_f32_e32 v40, v74, v56
	v_mul_f32_e32 v41, v75, v60
	v_mul_f32_e32 v46, v78, v64
	v_mul_f32_e32 v47, v79, v72
	v_bfe_u32 v44, v51, 16, 1
	v_bfe_u32 v48, v50, 16, 1
	v_bfe_u32 v52, v43, 16, 1
	v_bfe_u32 v54, v42, 16, 1
	v_add3_u32 v54, v42, v54, s68
	v_add3_u32 v52, v43, v52, s68
	v_add3_u32 v42, v50, v48, s68
	v_add3_u32 v43, v51, v44, s68
	v_bfe_u32 v44, v40, 16, 1
	v_bfe_u32 v48, v41, 16, 1
	v_bfe_u32 v50, v46, 16, 1
	v_bfe_u32 v51, v47, 16, 1
	v_add3_u32 v47, v47, v51, s68
	v_add3_u32 v46, v46, v50, s68
	v_add3_u32 v41, v41, v48, s68
	v_add3_u32 v40, v40, v44, s68
	v_lshrrev_b32_e32 v40, 16, v40
	v_lshrrev_b32_e32 v41, 16, v41
	v_lshrrev_b32_e32 v44, 16, v46
	v_lshrrev_b32_e32 v46, 16, v47
	v_add_co_u32_e32 v88, vcc, s61, v86
	v_and_or_b32 v43, v43, s69, v46
	v_and_or_b32 v42, v42, s69, v44
	v_and_or_b32 v41, v52, s69, v41
	v_and_or_b32 v40, v54, s69, v40
	v_addc_co_u32_e32 v89, vcc, 0, v87, vcc
	v_mov_b32_e32 v48, v45
	v_mov_b32_e32 v68, v53
	global_store_dwordx4 v[88:89], v[40:43], off
	v_mov_b32_e32 v60, v57
	v_mov_b32_e32 v72, v65
	v_pk_mul_f32 v[42:43], v[48:49], v[94:95]
	v_pk_mul_f32 v[46:47], v[68:69], v[92:93]
	v_pk_mul_f32 v[40:41], v[60:61], v[74:75]
	v_pk_mul_f32 v[44:45], v[72:73], v[78:79]
	v_bfe_u32 v48, v47, 16, 1
	v_bfe_u32 v49, v46, 16, 1
	v_bfe_u32 v50, v43, 16, 1
	v_bfe_u32 v51, v42, 16, 1
	v_add3_u32 v51, v42, v51, s68
	v_add3_u32 v50, v43, v50, s68
	v_add3_u32 v42, v46, v49, s68
	v_add3_u32 v43, v47, v48, s68
	v_bfe_u32 v46, v40, 16, 1
	v_bfe_u32 v47, v41, 16, 1
	v_bfe_u32 v48, v44, 16, 1
	v_bfe_u32 v49, v45, 16, 1
	v_add3_u32 v45, v45, v49, s68
	v_add3_u32 v44, v44, v48, s68
	v_add3_u32 v41, v41, v47, s68
	v_add3_u32 v40, v40, v46, s68
	v_lshrrev_b32_e32 v40, 16, v40
	v_lshrrev_b32_e32 v41, 16, v41
	v_lshrrev_b32_e32 v44, 16, v44
	v_lshrrev_b32_e32 v45, 16, v45
	v_and_or_b32 v43, v43, s69, v45
	v_and_or_b32 v42, v42, s69, v44
	v_and_or_b32 v41, v50, s69, v41
	v_and_or_b32 v40, v51, s69, v40
	s_waitcnt vmcnt(5)
	s_waitcnt vmcnt(3)
	global_store_dwordx4 v[88:89], v[40:43], off offset:2048
	v_mul_f32_e32 v44, v38, v26
	v_mul_f32_e32 v45, v39, v34
	s_waitcnt vmcnt(3)
	v_mul_f32_e32 v40, v2, v14
	v_mul_f32_e32 v41, v3, v18
	v_mul_f32_e32 v46, v76, v22
	v_mul_f32_e32 v47, v77, v30
	v_mul_f32_e32 v42, v80, v6
	v_mul_f32_e32 v43, v81, v10
	v_bfe_u32 v22, v40, 16, 1
	v_bfe_u32 v18, v42, 16, 1
	v_bfe_u32 v26, v41, 16, 1
	v_add3_u32 v22, v40, v22, s68
	v_bfe_u32 v14, v43, 16, 1
	v_add3_u32 v18, v42, v18, s68
	v_add3_u32 v26, v41, v26, s68
	v_lshrrev_b32_e32 v22, 16, v22
	v_cvt_pk_bf16_f32 v42, v44, v46
	v_mov_b32_e32 v10, v7
	v_add3_u32 v14, v43, v14, s68
	v_lshrrev_b32_e32 v26, 16, v26
	v_cvt_pk_bf16_f32 v43, v45, v47
	v_and_or_b32 v40, v18, s69, v22
	v_mov_b32_e32 v18, v15
	v_pk_mul_f32 v[6:7], v[10:11], v[80:81]
	v_mov_b32_e32 v34, v27
	v_mov_b32_e32 v30, v23
	v_and_or_b32 v41, v14, s69, v26
	v_pk_mul_f32 v[14:15], v[18:19], v[2:3]
	v_pk_mul_f32 v[10:11], v[34:35], v[38:39]
	v_pk_mul_f32 v[18:19], v[30:31], v[76:77]
	global_store_dwordx4 v[86:87], v[40:43], off offset:32
	s_nop 1
	v_cvt_pk_bf16_f32 v43, v11, v19
	s_nop 1
	v_cvt_pk_bf16_f32 v42, v10, v18
	v_cvt_pk_bf16_f32 v41, v15, v7
	v_cvt_pk_bf16_f32 v40, v14, v6
	v_mul_f32_e32 v10, v80, v8
	v_mul_f32_e32 v11, v81, v12
	v_mul_f32_e32 v18, v76, v24
	v_mul_f32_e32 v19, v77, v32
	v_mul_f32_e32 v6, v2, v16
	v_mul_f32_e32 v7, v3, v20
	v_mul_f32_e32 v14, v38, v28
	v_mul_f32_e32 v15, v39, v36
	v_bfe_u32 v16, v6, 16, 1
	v_bfe_u32 v20, v10, 16, 1
	v_add3_u32 v6, v6, v16, s68
	v_add3_u32 v10, v10, v20, s68
	v_lshrrev_b32_e32 v6, 16, v6
	v_mov_b32_e32 v32, v25
	global_store_dwordx4 v[86:87], v[40:43], off offset:2080
	v_mov_b32_e32 v20, v17
	s_nop 1
	v_cvt_pk_bf16_f32 v42, v14, v18
	v_cvt_pk_bf16_f32 v41, v7, v11
	v_and_or_b32 v40, v10, s69, v6
	v_mov_b32_e32 v12, v9
	v_pk_mul_f32 v[10:11], v[32:33], v[76:77]
	v_pk_mul_f32 v[2:3], v[20:21], v[2:3]
	v_pk_mul_f32 v[6:7], v[12:13], v[80:81]
	v_mov_b32_e32 v36, v29
	v_cvt_pk_bf16_f32 v43, v15, v19
	v_pk_mul_f32 v[8:9], v[36:37], v[38:39]
	v_lshl_add_u64 v[4:5], v[90:91], 0, s[16:17]
	v_cvt_pk_bf16_f32 v6, v2, v6
	v_add_co_u32_e32 v2, vcc, s75, v4
	v_cvt_pk_bf16_f32 v9, v9, v11
	v_cvt_pk_bf16_f32 v8, v8, v10
	v_cvt_pk_bf16_f32 v7, v3, v7
	v_addc_co_u32_e32 v3, vcc, 0, v5, vcc
	s_mov_b32 s8, 0xa000
	global_store_dwordx4 v[88:89], v[6:9], off offset:2080
	global_store_dwordx4 v[86:87], v[96:99], off
	global_store_dwordx4 v[88:89], v[40:43], off offset:32
	v_add_co_u32_e32 v6, vcc, s8, v90
	v_mov_b32_e32 v74, 1.0
	s_nop 0
	v_addc_co_u32_e32 v7, vcc, 0, v91, vcc
	global_load_dwordx4 v[50:53], v[2:3], off nt
	global_load_dwordx4 v[42:45], v[6:7], off offset:1280 nt
	global_load_dwordx4 v[54:57], v[6:7], off offset:2560 nt
	global_load_dwordx4 v[46:49], v[6:7], off offset:3840 nt
	v_add_co_u32_e32 v2, vcc, 0xb000, v90
	v_mov_b32_e32 v94, 1.0
	s_nop 0
	v_addc_co_u32_e32 v3, vcc, 0, v91, vcc
	v_add_co_u32_e32 v6, vcc, 0xc000, v90
	global_load_dwordx4 v[62:65], v[2:3], off offset:1024 nt
	global_load_dwordx4 v[58:61], v[2:3], off offset:2304 nt
	v_addc_co_u32_e32 v7, vcc, 0, v91, vcc
	global_load_dwordx4 v[70:73], v[2:3], off offset:3584 nt
	global_load_dwordx4 v[66:69], v[6:7], off offset:768 nt
	v_mov_b32_e32 v2, 1.0
	s_and_b64 vcc, exec, s[6:7]
	v_mov_b32_e32 v75, 1.0
	v_mov_b32_e32 v95, 1.0
	v_mov_b32_e32 v78, 1.0
	v_mov_b32_e32 v92, 1.0
	v_mov_b32_e32 v79, 1.0
	v_mov_b32_e32 v93, 1.0
	s_cbranch_vccnz .LBB0_600
	global_load_dwordx4 v[74:77], v84, s[48:49] offset:128
	global_load_dwordx4 v[78:81], v84, s[48:49] offset:144
	s_waitcnt vmcnt(1)
	v_mov_b32_e32 v94, v75
	v_mov_b32_e32 v75, v76
	v_mov_b32_e32 v95, v77
	s_waitcnt vmcnt(0)
	v_mov_b32_e32 v92, v79
	v_mov_b32_e32 v79, v80
	v_mov_b32_e32 v93, v81

.LBB0_602:
	s_waitcnt vmcnt(14)
	s_waitcnt vmcnt(12)
	s_waitcnt vmcnt(11)
	s_waitcnt vmcnt(9)
	v_mul_f32_e32 v40, v94, v42
	v_mul_f32_e32 v41, v95, v46
	v_mul_f32_e32 v90, v78, v62
	v_mul_f32_e32 v91, v79, v70
	s_waitcnt vmcnt(8)
	v_mul_f32_e32 v4, v74, v50
	v_mul_f32_e32 v5, v75, v54
	v_mul_f32_e32 v96, v92, v58
	v_mul_f32_e32 v97, v93, v66
	v_cvt_pk_bf16_f32 v98, v90, v96
	v_mov_b32_e32 v46, v43
	v_mov_b32_e32 v66, v59
	v_cvt_pk_bf16_f32 v99, v91, v97
	v_cvt_pk_bf16_f32 v97, v5, v41
	v_cvt_pk_bf16_f32 v96, v4, v40
	v_mov_b32_e32 v54, v51
	v_pk_mul_f32 v[40:41], v[46:47], v[94:95]
	v_mov_b32_e32 v70, v63
	v_pk_mul_f32 v[46:47], v[66:67], v[92:93]
	v_pk_mul_f32 v[4:5], v[54:55], v[74:75]
	v_pk_mul_f32 v[42:43], v[70:71], v[78:79]
	v_cvt_pk_bf16_f32 v43, v43, v47
	v_cvt_pk_bf16_f32 v42, v42, v46
	v_cvt_pk_bf16_f32 v41, v5, v41
	v_cvt_pk_bf16_f32 v40, v4, v40
	global_store_dwordx4 v[86:87], v[40:43], off offset:2112
	s_nop 1
	v_mul_f32_e32 v40, v94, v44
	s_nop 1
	v_mul_f32_e32 v41, v95, v48
	v_mul_f32_e32 v46, v92, v60
	v_mul_f32_e32 v47, v93, v68
	v_mul_f32_e32 v4, v74, v52
	v_mul_f32_e32 v5, v75, v56
	v_mul_f32_e32 v42, v78, v64
	v_mul_f32_e32 v43, v79, v72
	v_cvt_pk_bf16_f32 v43, v43, v47
	v_cvt_pk_bf16_f32 v42, v42, v46
	v_cvt_pk_bf16_f32 v41, v5, v41
	v_cvt_pk_bf16_f32 v40, v4, v40
	v_mov_b32_e32 v48, v45
	v_mov_b32_e32 v68, v61
	global_store_dwordx4 v[88:89], v[40:43], off offset:64
	v_mov_b32_e32 v56, v53
	v_mov_b32_e32 v72, v65
	v_pk_mul_f32 v[40:41], v[48:49], v[94:95]
	v_pk_mul_f32 v[44:45], v[68:69], v[92:93]
	v_pk_mul_f32 v[4:5], v[56:57], v[74:75]
	v_pk_mul_f32 v[42:43], v[72:73], v[78:79]
	v_cvt_pk_bf16_f32 v43, v43, v45
	v_cvt_pk_bf16_f32 v42, v42, v44
	v_cvt_pk_bf16_f32 v41, v5, v41
	v_cvt_pk_bf16_f32 v40, v4, v40
	global_store_dwordx4 v[88:89], v[40:43], off offset:2112
	s_waitcnt vmcnt(10)
	s_waitcnt vmcnt(8)
	s_waitcnt vmcnt(6)
	s_waitcnt vmcnt(4)
	v_mul_f32_e32 v42, v38, v18
	v_mul_f32_e32 v43, v39, v14
	s_waitcnt vmcnt(3)
	v_mul_f32_e32 v4, v2, v30
	v_mul_f32_e32 v5, v3, v34
	v_mul_f32_e32 v44, v76, v6
	v_mul_f32_e32 v45, v77, v10
	v_mul_f32_e32 v40, v80, v22
	v_mul_f32_e32 v41, v81, v26
	v_bfe_u32 v26, v5, 16, 1
	v_bfe_u32 v14, v41, 16, 1
	v_add3_u32 v5, v5, v26, s68
	v_add3_u32 v14, v41, v14, s68
	v_lshrrev_b32_e32 v5, 16, v5
	v_cvt_pk_bf16_f32 v43, v43, v45
	v_cvt_pk_bf16_f32 v42, v42, v44
	v_mov_b32_e32 v26, v23
	v_mov_b32_e32 v10, v7
	v_and_or_b32 v41, v14, s69, v5
	v_mov_b32_e32 v34, v31
	v_pk_mul_f32 v[22:23], v[26:27], v[80:81]
	v_pk_mul_f32 v[6:7], v[10:11], v[76:77]
	v_cvt_pk_bf16_f32 v40, v4, v40
	v_pk_mul_f32 v[4:5], v[34:35], v[2:3]
	v_mul_f32_e32 v14, v38, v19
	v_mul_f32_e32 v15, v39, v15
	v_bfe_u32 v10, v7, 16, 1
	v_bfe_u32 v18, v23, 16, 1
	v_add3_u32 v18, v23, v18, s68
	v_add3_u32 v7, v7, v10, s68
	v_bfe_u32 v11, v5, 16, 1
	v_bfe_u32 v23, v15, 16, 1
	v_add3_u32 v15, v15, v23, s68
	v_add3_u32 v5, v5, v11, s68
	v_lshrrev_b32_e32 v5, 16, v5
	v_lshrrev_b32_e32 v11, 16, v15
	v_and_or_b32 v7, v7, s69, v11
	v_cvt_pk_bf16_f32 v6, v14, v6
	v_and_or_b32 v5, v18, s69, v5
	v_cvt_pk_bf16_f32 v4, v4, v22
	global_store_dwordx4 v[86:87], v[4:7], off offset:2144
	s_nop 1
	v_mul_f32_e32 v6, v80, v24
	s_nop 1
	v_mul_f32_e32 v7, v81, v28
	v_mul_f32_e32 v14, v76, v8
	v_mul_f32_e32 v15, v77, v12
	v_mul_f32_e32 v4, v2, v32
	v_mul_f32_e32 v5, v3, v36
	v_mul_f32_e32 v10, v38, v20
	v_mul_f32_e32 v11, v39, v16
	v_bfe_u32 v8, v15, 16, 1
	v_bfe_u32 v12, v14, 16, 1
	v_bfe_u32 v16, v7, 16, 1
	v_bfe_u32 v18, v6, 16, 1
	v_add3_u32 v18, v6, v18, s68
	v_add3_u32 v16, v7, v16, s68
	v_add3_u32 v6, v14, v12, s68
	v_add3_u32 v7, v15, v8, s68
	v_bfe_u32 v8, v4, 16, 1
	v_bfe_u32 v12, v5, 16, 1
	v_bfe_u32 v14, v10, 16, 1
	v_bfe_u32 v15, v11, 16, 1
	v_add3_u32 v11, v11, v15, s68
	v_add3_u32 v10, v10, v14, s68
	v_add3_u32 v5, v5, v12, s68
	v_add3_u32 v4, v4, v8, s68
	v_lshrrev_b32_e32 v4, 16, v4
	v_lshrrev_b32_e32 v5, 16, v5
	v_lshrrev_b32_e32 v8, 16, v10
	v_lshrrev_b32_e32 v10, 16, v11
	v_mov_b32_e32 v36, v33
	v_and_or_b32 v7, v7, s69, v10
	v_and_or_b32 v6, v6, s69, v8
	v_and_or_b32 v5, v16, s69, v5
	v_and_or_b32 v4, v18, s69, v4
	v_pk_mul_f32 v[2:3], v[36:37], v[2:3]
	v_mov_b32_e32 v28, v25
	global_store_dwordx4 v[88:89], v[4:7], off offset:96
	v_mov_b32_e32 v8, v21
	v_mov_b32_e32 v12, v17
	v_pk_mul_f32 v[4:5], v[28:29], v[80:81]
	v_and_b32_sdwa v6, v3, v107 dst_sel:DWORD dst_unused:UNUSED_PAD src0_sel:WORD_1 src1_sel:DWORD
	v_and_b32_sdwa v7, v2, v107 dst_sel:DWORD dst_unused:UNUSED_PAD src0_sel:WORD_1 src1_sel:DWORD
	v_add3_u32 v2, v2, v7, s68
	v_add3_u32 v3, v3, v6, s68
	v_and_b32_sdwa v6, v5, v107 dst_sel:DWORD dst_unused:UNUSED_PAD src0_sel:WORD_1 src1_sel:DWORD
	v_and_b32_sdwa v7, v4, v107 dst_sel:DWORD dst_unused:UNUSED_PAD src0_sel:WORD_1 src1_sel:DWORD
	v_add3_u32 v5, v5, v6, s68
	v_add3_u32 v4, v4, v7, s68
	v_and_b32_e32 v5, 0xffff0000, v5
	v_and_b32_e32 v4, 0xffff0000, v4
	v_or_b32_sdwa v3, v5, v3 dst_sel:DWORD dst_unused:UNUSED_PAD src0_sel:DWORD src1_sel:WORD_1
	v_or_b32_sdwa v2, v4, v2 dst_sel:DWORD dst_unused:UNUSED_PAD src0_sel:DWORD src1_sel:WORD_1
	v_mov_b32_e32 v4, v38
	v_mov_b32_e32 v5, v76
	v_pk_mul_f32 v[4:5], v[8:9], v[4:5]
	v_mov_b32_e32 v76, v39
	v_and_b32_sdwa v6, v5, v107 dst_sel:DWORD dst_unused:UNUSED_PAD src0_sel:WORD_1 src1_sel:DWORD
	v_and_b32_sdwa v7, v4, v107 dst_sel:DWORD dst_unused:UNUSED_PAD src0_sel:WORD_1 src1_sel:DWORD
	v_add3_u32 v5, v5, v6, s68
	v_add3_u32 v4, v4, v7, s68
	v_pk_mul_f32 v[6:7], v[12:13], v[76:77]
	v_lshrrev_b32_e32 v4, 16, v4
	v_and_b32_sdwa v8, v6, v107 dst_sel:DWORD dst_unused:UNUSED_PAD src0_sel:WORD_1 src1_sel:DWORD
	v_and_or_b32 v4, v5, s69, v4
	v_and_b32_sdwa v5, v7, v107 dst_sel:DWORD dst_unused:UNUSED_PAD src0_sel:WORD_1 src1_sel:DWORD
	v_add3_u32 v6, v6, v8, s68
	v_add3_u32 v5, v7, v5, s68
	v_lshrrev_b32_e32 v6, 16, v6
	v_and_or_b32 v5, v5, s69, v6
	global_store_dwordx4 v[86:87], v[96:99], off offset:64
	global_store_dwordx4 v[86:87], v[40:43], off offset:96

.LBB0_642:
	s_waitcnt vmcnt(14)
	s_waitcnt vmcnt(12)
	s_waitcnt vmcnt(11)
	s_waitcnt vmcnt(9)
	v_mul_f32_e32 v32, v98, v42
	v_mul_f32_e32 v33, v99, v50
	v_mul_f32_e32 v90, v78, v62
	v_mul_f32_e32 v91, v79, v70
	s_waitcnt vmcnt(8)
	v_mul_f32_e32 v4, v74, v46
	v_mul_f32_e32 v5, v75, v58
	v_mul_f32_e32 v92, v96, v54
	v_mul_f32_e32 v93, v97, v66
	v_bfe_u32 v50, v33, 16, 1
	v_bfe_u32 v54, v32, 16, 1
	v_add3_u32 v32, v32, v54, s68
	v_add3_u32 v33, v33, v50, s68
	v_bfe_u32 v50, v4, 16, 1
	v_bfe_u32 v54, v5, 16, 1
	v_bfe_u32 v62, v91, 16, 1
	v_add3_u32 v5, v5, v54, s68
	v_add3_u32 v4, v4, v50, s68
	v_bfe_u32 v42, v93, 16, 1
	v_add3_u32 v62, v91, v62, s68
	v_lshrrev_b32_e32 v4, 16, v4
	v_lshrrev_b32_e32 v5, 16, v5
	v_cvt_pk_bf16_f32 v92, v90, v92
	v_mov_b32_e32 v50, v43
	v_mov_b32_e32 v66, v55
	v_add3_u32 v42, v93, v42, s68
	v_lshrrev_b32_e32 v54, 16, v62
	v_and_or_b32 v91, v33, s69, v5
	v_and_or_b32 v90, v32, s69, v4
	v_mov_b32_e32 v58, v47
	v_pk_mul_f32 v[32:33], v[50:51], v[98:99]
	v_mov_b32_e32 v70, v63
	v_pk_mul_f32 v[46:47], v[66:67], v[96:97]
	v_and_or_b32 v93, v42, s69, v54
	v_pk_mul_f32 v[4:5], v[58:59], v[74:75]
	v_pk_mul_f32 v[42:43], v[70:71], v[78:79]
	global_store_dwordx4 v[86:87], v[90:93], off offset:64
	s_mov_b64 s[50:51], 0
	s_nop 0
	v_cvt_pk_bf16_f32 v93, v43, v47
	v_cvt_pk_bf16_f32 v92, v42, v46
	v_cvt_pk_bf16_f32 v91, v5, v33
	v_cvt_pk_bf16_f32 v90, v4, v32
	v_mul_f32_e32 v32, v98, v44
	v_mul_f32_e32 v33, v99, v52
	v_mul_f32_e32 v46, v96, v56
	v_mul_f32_e32 v47, v97, v68
	v_mul_f32_e32 v4, v74, v48
	v_mul_f32_e32 v5, v75, v60
	v_mul_f32_e32 v42, v78, v64
	v_mul_f32_e32 v43, v79, v72
	v_mov_b32_e32 v52, v45
	v_mov_b32_e32 v68, v57
	global_store_dwordx4 v[86:87], v[90:93], off offset:2112
	v_mov_b32_e32 v60, v49
	s_nop 1
	v_cvt_pk_bf16_f32 v93, v43, v47
	v_cvt_pk_bf16_f32 v91, v5, v33
	v_cvt_pk_bf16_f32 v90, v4, v32
	v_pk_mul_f32 v[32:33], v[52:53], v[98:99]
	v_mov_b32_e32 v72, v65
	v_pk_mul_f32 v[44:45], v[68:69], v[96:97]
	v_cvt_pk_bf16_f32 v92, v42, v46
	v_pk_mul_f32 v[4:5], v[60:61], v[74:75]
	v_pk_mul_f32 v[42:43], v[72:73], v[78:79]
	v_cvt_pk_bf16_f32 v45, v43, v45
	v_cvt_pk_bf16_f32 v44, v42, v44
	v_cvt_pk_bf16_f32 v43, v5, v33
	v_cvt_pk_bf16_f32 v42, v4, v32
	s_waitcnt vmcnt(8)
	s_waitcnt vmcnt(6)
	global_store_dwordx4 v[88:89], v[42:45], off offset:2112
	v_mul_f32_e32 v32, v80, v22
	v_mul_f32_e32 v33, v81, v34
	s_waitcnt vmcnt(6)
	s_waitcnt vmcnt(4)
	v_mul_f32_e32 v42, v30, v18
	v_mul_f32_e32 v43, v31, v10
	s_waitcnt vmcnt(3)
	v_mul_f32_e32 v4, v2, v26
	v_mul_f32_e32 v5, v3, v38
	v_mul_f32_e32 v44, v76, v14
	v_mul_f32_e32 v45, v77, v6
	v_bfe_u32 v18, v32, 16, 1
	v_add3_u32 v18, v32, v18, s68
	v_bfe_u32 v22, v4, 16, 1
	v_add3_u32 v4, v4, v22, s68
	v_cvt_pk_bf16_f32 v45, v43, v45
	v_mov_b32_e32 v34, v23
	v_lshrrev_b32_e32 v4, 16, v4
	v_cvt_pk_bf16_f32 v44, v42, v44
	v_mov_b32_e32 v38, v27
	v_pk_mul_f32 v[22:23], v[34:35], v[80:81]
	v_mul_f32_e32 v6, v76, v15
	v_mul_f32_e32 v7, v77, v7
	v_cvt_pk_bf16_f32 v43, v5, v33
	v_and_or_b32 v42, v18, s69, v4
	v_pk_mul_f32 v[4:5], v[38:39], v[2:3]
	v_mul_f32_e32 v10, v30, v19
	v_mul_f32_e32 v11, v31, v11
	v_cvt_pk_bf16_f32 v7, v11, v7
	v_cvt_pk_bf16_f32 v6, v10, v6
	v_cvt_pk_bf16_f32 v5, v5, v23
	v_cvt_pk_bf16_f32 v4, v4, v22
	global_store_dwordx4 v[86:87], v[4:7], off offset:2144
	s_nop 1
	v_mul_f32_e32 v6, v80, v24
	s_nop 1
	v_mul_f32_e32 v7, v81, v36
	v_mul_f32_e32 v14, v76, v16
	v_mul_f32_e32 v15, v77, v8
	v_mul_f32_e32 v4, v2, v28
	v_mul_f32_e32 v5, v3, v40
	v_mul_f32_e32 v10, v30, v20
	v_mul_f32_e32 v11, v31, v12
	v_bfe_u32 v8, v15, 16, 1
	v_bfe_u32 v12, v14, 16, 1
	v_bfe_u32 v16, v7, 16, 1
	v_bfe_u32 v18, v6, 16, 1
	v_add3_u32 v18, v6, v18, s68
	v_add3_u32 v16, v7, v16, s68
	v_add3_u32 v6, v14, v12, s68
	v_add3_u32 v7, v15, v8, s68
	v_bfe_u32 v8, v4, 16, 1
	v_bfe_u32 v12, v5, 16, 1
	v_bfe_u32 v14, v10, 16, 1
	v_bfe_u32 v15, v11, 16, 1
	v_add3_u32 v11, v11, v15, s68
	v_add3_u32 v10, v10, v14, s68
	v_add3_u32 v5, v5, v12, s68
	v_add3_u32 v4, v4, v8, s68
	v_lshrrev_b32_e32 v4, 16, v4
	v_lshrrev_b32_e32 v5, 16, v5
	v_lshrrev_b32_e32 v8, 16, v10
	v_lshrrev_b32_e32 v10, 16, v11
	v_mov_b32_e32 v40, v29
	v_and_or_b32 v7, v7, s69, v10
	v_and_or_b32 v6, v6, s69, v8
	v_and_or_b32 v5, v16, s69, v5
	v_and_or_b32 v4, v18, s69, v4
	v_pk_mul_f32 v[2:3], v[40:41], v[2:3]
	v_mov_b32_e32 v36, v25
	global_store_dwordx4 v[88:89], v[4:7], off offset:96
	v_mov_b32_e32 v16, v21
	v_mov_b32_e32 v8, v13
	v_pk_mul_f32 v[4:5], v[36:37], v[80:81]
	v_and_b32_sdwa v6, v3, v107 dst_sel:DWORD dst_unused:UNUSED_PAD src0_sel:WORD_1 src1_sel:DWORD
	v_and_b32_sdwa v7, v2, v107 dst_sel:DWORD dst_unused:UNUSED_PAD src0_sel:WORD_1 src1_sel:DWORD
	v_add3_u32 v2, v2, v7, s68
	v_add3_u32 v3, v3, v6, s68
	v_and_b32_sdwa v6, v5, v107 dst_sel:DWORD dst_unused:UNUSED_PAD src0_sel:WORD_1 src1_sel:DWORD
	v_and_b32_sdwa v7, v4, v107 dst_sel:DWORD dst_unused:UNUSED_PAD src0_sel:WORD_1 src1_sel:DWORD
	v_add3_u32 v5, v5, v6, s68
	v_add3_u32 v4, v4, v7, s68
	v_and_b32_e32 v5, 0xffff0000, v5
	v_and_b32_e32 v4, 0xffff0000, v4
	v_or_b32_sdwa v3, v5, v3 dst_sel:DWORD dst_unused:UNUSED_PAD src0_sel:DWORD src1_sel:WORD_1
	v_or_b32_sdwa v2, v4, v2 dst_sel:DWORD dst_unused:UNUSED_PAD src0_sel:DWORD src1_sel:WORD_1
	v_mov_b32_e32 v4, v30
	v_mov_b32_e32 v5, v76
	v_pk_mul_f32 v[4:5], v[16:17], v[4:5]
	v_mov_b32_e32 v76, v31
	v_and_b32_sdwa v6, v5, v107 dst_sel:DWORD dst_unused:UNUSED_PAD src0_sel:WORD_1 src1_sel:DWORD
	v_and_b32_sdwa v7, v4, v107 dst_sel:DWORD dst_unused:UNUSED_PAD src0_sel:WORD_1 src1_sel:DWORD
	v_add3_u32 v5, v5, v6, s68
	v_add3_u32 v4, v4, v7, s68
	v_pk_mul_f32 v[6:7], v[8:9], v[76:77]
	v_lshrrev_b32_e32 v4, 16, v4
	v_and_b32_sdwa v8, v6, v107 dst_sel:DWORD dst_unused:UNUSED_PAD src0_sel:WORD_1 src1_sel:DWORD
	v_and_or_b32 v4, v5, s69, v4
	v_and_b32_sdwa v5, v7, v107 dst_sel:DWORD dst_unused:UNUSED_PAD src0_sel:WORD_1 src1_sel:DWORD
	v_add3_u32 v6, v6, v8, s68
	v_add3_u32 v5, v7, v5, s68
	v_lshrrev_b32_e32 v6, 16, v6
	v_and_or_b32 v5, v5, s69, v6
	global_store_dwordx4 v[88:89], v[90:93], off offset:64
	global_store_dwordx4 v[86:87], v[42:45], off offset:96
